# ffn_up: MFMA operands swapped, SwiGLU epilogue with v_rcp+Newton instead of IEEE div sequence, packed bf16 ds_write_b64 staging; same packed staging in win/gemm_f32
# speedup vs baseline: 1.1045x; 1.0164x over previous
; template <int MI, int NJ> ...
;     ...
;   for (int kt = 0; kt < nk; ++kt) {
;     const int buf = kt & 1;
;     {
;       G8STORE(buf ^ 1);
;       const u16* ga_ = (kt + 2 < nk) ? Ag + (kt + 2) * 64 : Ag + nAoff;
;       const u16* gb_ = (kt + 2 < nk) ? Bg + (kt + 2) * 64 : Bg + nBoff;
;       G8LOADP(ga_, gb_);
;     }
;     __builtin_amdgcn_sched_barrier(0);
;     __builtin_amdgcn_s_setprio(1);
;     const u16* a = ra_ + buf * AROWS * 64;
;     const u16* b = rb_ + buf * BROWS * 64;
; #pragma unroll
;     for (int ks = 0; ks < 2; ++ks) {
;       const u16* a_ = ks ? a + dsw : a;
;       const u16* b_ = ks ? b + dsw : b;
;       bf16x8 bfr[NJ];
; #pragma unroll
;       for (int j = 0; j < NJ; ++j) bfr[j] = *(const bf16x8*)(b_ + j * 16 * 64);
; #pragma unroll
;       for (int ih = 0; ih < MI / 4; ++ih) {
;         bf16x8 af[4];
; #pragma unroll
;         for (int i = 0; i < 4; ++i) af[i] = *(const bf16x8*)(a_ + (ih * 4 + i) * 16 * 64);
; #pragma unroll
;         for (int i = 0; i < 4; ++i)
; #pragma unroll
;           for (int j = 0; j < NJ; ++j) acc[ih * 4 + i][j] = mfma16(af[i], bfr[j], acc[ih * 4 + i][j]);
;       }
;     }
;     __builtin_amdgcn_s_setprio(0);
;     __builtin_amdgcn_sched_barrier(0);
;     __syncthreads();
;   }
.LBB0_470:
	s_and_b32 s38, s11, 0x4000
	s_xor_b32 s39, s38, 0x4000
	s_lshl_b32 s39, s39, 1
	v_add_u32_e32 v228, s39, v185
	v_add_u32_e32 v229, s39, v186
	s_cmp_lt_u32 s37, 14
	s_cselect_b32 s49, s21, s13
	s_cselect_b32 s48, s20, s12
	s_cselect_b32 s51, s21, s47
	s_cselect_b32 s50, s20, s46
	s_lshl_b64 s[48:49], s[48:49], 1
	s_lshl_b64 s[50:51], s[50:51], 1
	s_add_u32 s52, s62, s48
	s_addc_u32 s53, s63, s49
	s_add_u32 s66, s64, s50
	s_addc_u32 s67, s65, s51
	s_setprio 1
	s_lshl_b32 s38, s38, 1
	v_add_u32_e32 v0, s38, v187
	v_add_u32_e32 v191, s38, v188
	ds_read_b128 v[166:169], v191
	ds_read_b128 v[162:165], v0
	ds_read_b128 v[170:173], v191 offset:2048
	ds_read_b128 v[192:195], v191 offset:4096
	ds_read_b128 v[196:199], v191 offset:6144
	ds_read_b128 v[204:207], v0 offset:2048
	ds_read_b128 v[208:211], v0 offset:4096
	v_add_u32_e32 v191, v191, v190
	s_waitcnt lgkmcnt(5)
	v_mfma_f32_16x16x32_bf16 v[158:161], v[166:169], v[162:165], v[158:161]
	s_waitcnt lgkmcnt(4)
	v_mfma_f32_16x16x32_bf16 v[154:157], v[170:173], v[162:165], v[154:157]
	s_waitcnt lgkmcnt(3)
	v_mfma_f32_16x16x32_bf16 v[150:153], v[192:195], v[162:165], v[150:153]
	s_waitcnt lgkmcnt(2)
	v_mfma_f32_16x16x32_bf16 v[146:149], v[196:199], v[162:165], v[146:149]
	ds_read_b128 v[162:165], v0 offset:6144
	s_waitcnt lgkmcnt(2)
	v_mfma_f32_16x16x32_bf16 v[142:145], v[166:169], v[204:207], v[142:145]
	v_mfma_f32_16x16x32_bf16 v[138:141], v[170:173], v[204:207], v[138:141]
	v_mfma_f32_16x16x32_bf16 v[134:137], v[192:195], v[204:207], v[134:137]
	v_mfma_f32_16x16x32_bf16 v[130:133], v[196:199], v[204:207], v[130:133]
	ds_read_b128 v[204:207], v0 offset:8192
	s_waitcnt vmcnt(7)
	ds_write_b128 v228, v[10:13]
	global_load_dwordx4 v[10:13], v234, s[52:53]
	s_waitcnt lgkmcnt(3)
	v_mfma_f32_16x16x32_bf16 v[126:129], v[166:169], v[208:211], v[126:129]
	v_mfma_f32_16x16x32_bf16 v[122:125], v[170:173], v[208:211], v[122:125]
	v_mfma_f32_16x16x32_bf16 v[118:121], v[192:195], v[208:211], v[118:121]
	v_mfma_f32_16x16x32_bf16 v[114:117], v[196:199], v[208:211], v[114:117]
	ds_read_b128 v[208:211], v0 offset:10240
	s_waitcnt vmcnt(7)
	ds_write_b128 v228, v[2:5] offset:8192
	global_load_dwordx4 v[2:5], v235, s[52:53]
	ds_read_b128 v[212:215], v191
	ds_read_b128 v[216:219], v191 offset:2048
	s_waitcnt lgkmcnt(6)
	v_mfma_f32_16x16x32_bf16 v[110:113], v[166:169], v[162:165], v[110:113]
	v_mfma_f32_16x16x32_bf16 v[106:109], v[170:173], v[162:165], v[106:109]
	v_mfma_f32_16x16x32_bf16 v[102:105], v[192:195], v[162:165], v[102:105]
	v_mfma_f32_16x16x32_bf16 v[98:101], v[196:199], v[162:165], v[98:101]
	ds_read_b128 v[162:165], v0 offset:12288
	s_waitcnt vmcnt(7)
	ds_write_b128 v228, v[6:9] offset:16384
	global_load_dwordx4 v[6:9], v236, s[52:53]
	ds_read_b128 v[220:223], v191 offset:4096
	ds_read_b128 v[224:227], v191 offset:6144
	s_waitcnt lgkmcnt(9)
	v_mfma_f32_16x16x32_bf16 v[94:97], v[166:169], v[204:207], v[94:97]
	v_mfma_f32_16x16x32_bf16 v[90:93], v[170:173], v[204:207], v[90:93]
	v_mfma_f32_16x16x32_bf16 v[86:89], v[192:195], v[204:207], v[86:89]
	v_mfma_f32_16x16x32_bf16 v[82:85], v[196:199], v[204:207], v[82:85]
	ds_read_b128 v[204:207], v0 offset:14336
	s_waitcnt vmcnt(7)
	ds_write_b128 v228, v[18:21] offset:24576
	global_load_dwordx4 v[18:21], v237, s[52:53]
	s_waitcnt lgkmcnt(9)
	v_mfma_f32_16x16x32_bf16 v[78:81], v[166:169], v[208:211], v[78:81]
	v_mfma_f32_16x16x32_bf16 v[74:77], v[170:173], v[208:211], v[74:77]
	v_mfma_f32_16x16x32_bf16 v[70:73], v[192:195], v[208:211], v[70:73]
	v_mfma_f32_16x16x32_bf16 v[66:69], v[196:199], v[208:211], v[66:69]
	v_add_u32_e32 v0, v0, v190
	ds_read_b128 v[208:211], v0
	s_waitcnt vmcnt(7)
	ds_write_b128 v229, v[14:17]
	global_load_dwordx4 v[14:17], v234, s[66:67]
	s_waitcnt lgkmcnt(7)
	v_mfma_f32_16x16x32_bf16 v[62:65], v[166:169], v[162:165], v[62:65]
	v_mfma_f32_16x16x32_bf16 v[58:61], v[170:173], v[162:165], v[58:61]
	v_mfma_f32_16x16x32_bf16 v[54:57], v[192:195], v[162:165], v[54:57]
	v_mfma_f32_16x16x32_bf16 v[50:53], v[196:199], v[162:165], v[50:53]
	ds_read_b128 v[162:165], v0 offset:2048
	s_waitcnt vmcnt(7)
	ds_write_b128 v229, v[22:25] offset:8192
	global_load_dwordx4 v[22:25], v235, s[66:67]
	s_waitcnt lgkmcnt(5)
	v_mfma_f32_16x16x32_bf16 v[46:49], v[166:169], v[204:207], v[46:49]
	v_mfma_f32_16x16x32_bf16 v[42:45], v[170:173], v[204:207], v[42:45]
	v_mfma_f32_16x16x32_bf16 v[38:41], v[192:195], v[204:207], v[38:41]
	v_mfma_f32_16x16x32_bf16 v[34:37], v[196:199], v[204:207], v[34:37]
	ds_read_b128 v[204:207], v0 offset:4096
	s_waitcnt vmcnt(7)
	ds_write_b128 v229, v[26:29] offset:16384
	global_load_dwordx4 v[26:29], v236, s[66:67]
	s_waitcnt lgkmcnt(5)
	v_mfma_f32_16x16x32_bf16 v[158:161], v[212:215], v[208:211], v[158:161]
	v_mfma_f32_16x16x32_bf16 v[154:157], v[216:219], v[208:211], v[154:157]
	v_mfma_f32_16x16x32_bf16 v[150:153], v[220:223], v[208:211], v[150:153]
	v_mfma_f32_16x16x32_bf16 v[146:149], v[224:227], v[208:211], v[146:149]
	ds_read_b128 v[208:211], v0 offset:6144
	s_waitcnt vmcnt(7)
	ds_write_b128 v229, v[30:33] offset:24576
	global_load_dwordx4 v[30:33], v237, s[66:67]
	s_waitcnt lgkmcnt(5)
	v_mfma_f32_16x16x32_bf16 v[142:145], v[212:215], v[162:165], v[142:145]
	v_mfma_f32_16x16x32_bf16 v[138:141], v[216:219], v[162:165], v[138:141]
	v_mfma_f32_16x16x32_bf16 v[134:137], v[220:223], v[162:165], v[134:137]
	v_mfma_f32_16x16x32_bf16 v[130:133], v[224:227], v[162:165], v[130:133]
	ds_read_b128 v[162:165], v0 offset:8192
	s_waitcnt lgkmcnt(4)
	v_mfma_f32_16x16x32_bf16 v[126:129], v[212:215], v[204:207], v[126:129]
	v_mfma_f32_16x16x32_bf16 v[122:125], v[216:219], v[204:207], v[122:125]
	v_mfma_f32_16x16x32_bf16 v[118:121], v[220:223], v[204:207], v[118:121]
	v_mfma_f32_16x16x32_bf16 v[114:117], v[224:227], v[204:207], v[114:117]
	ds_read_b128 v[204:207], v0 offset:10240
	s_waitcnt lgkmcnt(3)
; template <int MI, int NJ> ...
;     ...
; #pragma unroll
;     for (int ks = 0; ks < 2; ++ks) {
;       const u16* a_ = ks ? a + dsw : a;
;       const u16* b_ = ks ? b + dsw : b;
;       bf16x8 bfr[NJ];
; #pragma unroll
;       for (int j = 0; j < NJ; ++j) bfr[j] = *(const bf16x8*)(b_ + j * 16 * 64);
; #pragma unroll
;       for (int ih = 0; ih < MI / 4; ++ih) {
;         bf16x8 af[4];
; #pragma unroll
;         for (int i = 0; i < 4; ++i) af[i] = *(const bf16x8*)(a_ + (ih * 4 + i) * 16 * 64);
; #pragma unroll
;         for (int i = 0; i < 4; ++i)
; #pragma unroll
;           for (int j = 0; j < NJ; ++j) acc[ih * 4 + i][j] = mfma16(af[i], bfr[j], acc[ih * 4 + i][j]);
;       }
;     }
;     __builtin_amdgcn_s_setprio(0);
;     __builtin_amdgcn_sched_barrier(0);
;     __syncthreads();
;   }
; __device__ __forceinline__ void phase_win(const Params& p, int part, u16* smem, volatile LAS unsigned* vb_) {
;     ...
; #pragma unroll
;     for (int i = 0; i < 8; ++i)
; #pragma unroll
;       for (int j = 0; j < 4; ++j)
; #pragma unroll
;         for (int r = 0; r < 4; ++r)
;           smem[(wm * 128 + i * 16 + (lane >> 4) * 4 + r) * 264 + wn * 64 + j * 16 + (lane & 15)] = f2bf(acc[i][j][r]);
;     __syncthreads();
	v_mfma_f32_16x16x32_bf16 v[110:113], v[212:215], v[208:211], v[110:113]
	v_mfma_f32_16x16x32_bf16 v[106:109], v[216:219], v[208:211], v[106:109]
	v_mfma_f32_16x16x32_bf16 v[102:105], v[220:223], v[208:211], v[102:105]
	v_mfma_f32_16x16x32_bf16 v[98:101], v[224:227], v[208:211], v[98:101]
	ds_read_b128 v[208:211], v0 offset:12288
	s_waitcnt lgkmcnt(2)
	v_mfma_f32_16x16x32_bf16 v[94:97], v[212:215], v[162:165], v[94:97]
	v_mfma_f32_16x16x32_bf16 v[90:93], v[216:219], v[162:165], v[90:93]
	v_mfma_f32_16x16x32_bf16 v[86:89], v[220:223], v[162:165], v[86:89]
	v_mfma_f32_16x16x32_bf16 v[82:85], v[224:227], v[162:165], v[82:85]
	ds_read_b128 v[162:165], v0 offset:14336
	s_waitcnt lgkmcnt(2)
	v_mfma_f32_16x16x32_bf16 v[78:81], v[212:215], v[204:207], v[78:81]
	v_mfma_f32_16x16x32_bf16 v[74:77], v[216:219], v[204:207], v[74:77]
	v_mfma_f32_16x16x32_bf16 v[70:73], v[220:223], v[204:207], v[70:73]
	v_mfma_f32_16x16x32_bf16 v[66:69], v[224:227], v[204:207], v[66:69]
	s_waitcnt lgkmcnt(1)
	v_mfma_f32_16x16x32_bf16 v[62:65], v[212:215], v[208:211], v[62:65]
	v_mfma_f32_16x16x32_bf16 v[58:61], v[216:219], v[208:211], v[58:61]
	v_mfma_f32_16x16x32_bf16 v[54:57], v[220:223], v[208:211], v[54:57]
	v_mfma_f32_16x16x32_bf16 v[50:53], v[224:227], v[208:211], v[50:53]
	s_waitcnt lgkmcnt(0)
	v_mfma_f32_16x16x32_bf16 v[46:49], v[212:215], v[162:165], v[46:49]
	v_mfma_f32_16x16x32_bf16 v[42:45], v[216:219], v[162:165], v[42:45]
	v_mfma_f32_16x16x32_bf16 v[38:41], v[220:223], v[162:165], v[38:41]
	v_mfma_f32_16x16x32_bf16 v[34:37], v[224:227], v[162:165], v[34:37]
	s_setprio 0
	s_add_i32 s37, s37, 1
	s_add_u32 s20, s20, 64
	s_addc_u32 s21, s21, 0
	s_addk_i32 s11, 0x4000
	s_cmpk_lg_i32 s20, 0x480
	s_barrier
	s_cbranch_scc1 .LBB0_470
	v_and_b32_e32 v228, 15, v175
	v_bfe_u32 v229, v175, 8, 1
	v_lshl_or_b32 v228, v229, 7, v228
	v_mul_u32_u24_e32 v228, 0x210, v228
	v_bfe_u32 v229, v175, 6, 2
	v_lshl_add_u32 v228, v229, 7, v228
	v_bfe_u32 v229, v175, 4, 2
	v_lshl_add_u32 v228, v229, 3, v228
	v_cvt_pk_bf16_f32 v158, v158, v159
	v_cvt_pk_bf16_f32 v159, v160, v161
	v_cvt_pk_bf16_f32 v154, v154, v155
	v_cvt_pk_bf16_f32 v155, v156, v157
	v_cvt_pk_bf16_f32 v150, v150, v151
	v_cvt_pk_bf16_f32 v151, v152, v153
	v_cvt_pk_bf16_f32 v146, v146, v147
	v_cvt_pk_bf16_f32 v147, v148, v149
	ds_write_b64 v228, v[158:159]
	ds_write_b64 v228, v[154:155] offset:32
	ds_write_b64 v228, v[150:151] offset:64
	ds_write_b64 v228, v[146:147] offset:96
	v_cvt_pk_bf16_f32 v142, v142, v143
	v_cvt_pk_bf16_f32 v143, v144, v145
	v_cvt_pk_bf16_f32 v138, v138, v139
	v_cvt_pk_bf16_f32 v139, v140, v141
	v_cvt_pk_bf16_f32 v134, v134, v135
	v_cvt_pk_bf16_f32 v135, v136, v137
	v_cvt_pk_bf16_f32 v130, v130, v131
	v_cvt_pk_bf16_f32 v131, v132, v133
	ds_write_b64 v228, v[142:143] offset:8448
	ds_write_b64 v228, v[138:139] offset:8480
	ds_write_b64 v228, v[134:135] offset:8512
	ds_write_b64 v228, v[130:131] offset:8544
	v_cvt_pk_bf16_f32 v126, v126, v127
	v_cvt_pk_bf16_f32 v127, v128, v129
	v_cvt_pk_bf16_f32 v122, v122, v123
	v_cvt_pk_bf16_f32 v123, v124, v125
	v_cvt_pk_bf16_f32 v118, v118, v119
	v_cvt_pk_bf16_f32 v119, v120, v121
	v_cvt_pk_bf16_f32 v114, v114, v115
	v_cvt_pk_bf16_f32 v115, v116, v117
	ds_write_b64 v228, v[126:127] offset:16896
	ds_write_b64 v228, v[122:123] offset:16928
	ds_write_b64 v228, v[118:119] offset:16960
	ds_write_b64 v228, v[114:115] offset:16992
	v_cvt_pk_bf16_f32 v110, v110, v111
	v_cvt_pk_bf16_f32 v111, v112, v113
	v_cvt_pk_bf16_f32 v106, v106, v107
	v_cvt_pk_bf16_f32 v107, v108, v109
	v_cvt_pk_bf16_f32 v102, v102, v103
	v_cvt_pk_bf16_f32 v103, v104, v105
	v_cvt_pk_bf16_f32 v98, v98, v99
	v_cvt_pk_bf16_f32 v99, v100, v101
	ds_write_b64 v228, v[110:111] offset:25344
	ds_write_b64 v228, v[106:107] offset:25376
	ds_write_b64 v228, v[102:103] offset:25408
	ds_write_b64 v228, v[98:99] offset:25440
	v_cvt_pk_bf16_f32 v94, v94, v95
	v_cvt_pk_bf16_f32 v95, v96, v97
	v_cvt_pk_bf16_f32 v90, v90, v91
	v_cvt_pk_bf16_f32 v91, v92, v93
	v_cvt_pk_bf16_f32 v86, v86, v87
	v_cvt_pk_bf16_f32 v87, v88, v89
	v_cvt_pk_bf16_f32 v82, v82, v83
	v_cvt_pk_bf16_f32 v83, v84, v85
	ds_write_b64 v228, v[94:95] offset:33792
	ds_write_b64 v228, v[90:91] offset:33824
	ds_write_b64 v228, v[86:87] offset:33856
	ds_write_b64 v228, v[82:83] offset:33888
	v_cvt_pk_bf16_f32 v78, v78, v79
	v_cvt_pk_bf16_f32 v79, v80, v81
	v_cvt_pk_bf16_f32 v74, v74, v75
	v_cvt_pk_bf16_f32 v75, v76, v77
	v_cvt_pk_bf16_f32 v70, v70, v71
	v_cvt_pk_bf16_f32 v71, v72, v73
	v_cvt_pk_bf16_f32 v66, v66, v67
	v_cvt_pk_bf16_f32 v67, v68, v69
	ds_write_b64 v228, v[78:79] offset:42240
	ds_write_b64 v228, v[74:75] offset:42272
	ds_write_b64 v228, v[70:71] offset:42304
	ds_write_b64 v228, v[66:67] offset:42336
	v_cvt_pk_bf16_f32 v62, v62, v63
	v_cvt_pk_bf16_f32 v63, v64, v65
	v_cvt_pk_bf16_f32 v58, v58, v59
	v_cvt_pk_bf16_f32 v59, v60, v61
	v_cvt_pk_bf16_f32 v54, v54, v55
	v_cvt_pk_bf16_f32 v55, v56, v57
	v_cvt_pk_bf16_f32 v50, v50, v51
	v_cvt_pk_bf16_f32 v51, v52, v53
	ds_write_b64 v228, v[62:63] offset:50688
	ds_write_b64 v228, v[58:59] offset:50720
	ds_write_b64 v228, v[54:55] offset:50752
	ds_write_b64 v228, v[50:51] offset:50784
	v_cvt_pk_bf16_f32 v46, v46, v47
	v_cvt_pk_bf16_f32 v47, v48, v49
	v_cvt_pk_bf16_f32 v42, v42, v43
	v_cvt_pk_bf16_f32 v43, v44, v45
	v_cvt_pk_bf16_f32 v38, v38, v39
	v_cvt_pk_bf16_f32 v39, v40, v41
	v_cvt_pk_bf16_f32 v34, v34, v35
	v_cvt_pk_bf16_f32 v35, v36, v37
	ds_write_b64 v228, v[46:47] offset:59136
	ds_write_b64 v228, v[42:43] offset:59168
	ds_write_b64 v228, v[38:39] offset:59200
	ds_write_b64 v228, v[34:35] offset:59232
	v_mov_b32_e32 v43, v175
	s_waitcnt lgkmcnt(0)
	s_barrier
; #define RTID opaque_tid()
; __device__ __forceinline__ void phase_win(const Params& p, int part, u16* smem, volatile LAS unsigned* vb_) {
;     ...
;     const int tid2 = RTID;
; #pragma unroll
;     for (int k = 0; k < 16; ++k) {
;       const int c = tid2 + 512 * k;
;       const int row = c >> 5, ch = c & 31;
;       const uint4 v = *(const uint4*)(smem + row * 264 + ch * 8);
;       u16* d_ = (ch < 16) ? dstA : dstB;
;       const int l_ = (ch < 16) ? ldA : ldB;
;       *(uint4*)(d_ + (size_t)(mt * 256 + row) * l_ + (ch & 15) * 8) = v;
;     }
;     __syncthreads();
	s_mov_b32 s38, s36
	v_and_b32_e32 v0, 31, v43
	v_lshlrev_b32_e32 v42, 4, v0
	v_cmp_gt_u32_e32 vcc, 16, v0
	v_mov_b32_e32 v0, 0x100
	s_nop 0
	v_cndmask_b32_e64 v0, v0, 0, vcc
	v_lshl_add_u64 v[34:35], s[44:45], 0, v[0:1]
	v_lshlrev_b32_e32 v0, 4, v43
	v_and_b32_e32 v0, 0xf0, v0
	v_lshl_add_u64 v[44:45], v[34:35], 0, v[0:1]
	v_ashrrev_i32_e32 v0, 5, v43
	v_mad_u64_u32 v[34:35], s[12:13], v0, s2, v[42:43]
	v_add_u32_e32 v0, s10, v0
	ds_read_b128 v[34:37], v34
	v_ashrrev_i32_e32 v38, 31, v0
	v_mul_lo_u32 v40, s0, v38
	v_mul_lo_u32 v41, s1, v0
	v_mad_u64_u32 v[38:39], s[12:13], s0, v0, 0
	v_add_u32_e32 v0, 0x200, v43
	v_add3_u32 v39, v39, v40, v41
	v_ashrrev_i32_e32 v0, 5, v0
	v_lshl_add_u64 v[46:47], v[38:39], 1, v[44:45]
	v_mad_u64_u32 v[38:39], s[12:13], v0, s2, v[42:43]
	ds_read_b128 v[38:41], v38
	v_add_u32_e32 v0, s10, v0
	s_waitcnt lgkmcnt(1)
	global_store_dwordx4 v[46:47], v[34:37], off
	s_and_b64 vcc, exec, s[42:43]
	s_nop 0
	v_ashrrev_i32_e32 v34, 31, v0
	v_mul_lo_u32 v36, s0, v34
	v_mul_lo_u32 v37, s1, v0
	v_mad_u64_u32 v[34:35], s[12:13], s0, v0, 0
	v_add3_u32 v35, v35, v36, v37
	v_add_u32_e32 v0, 0x400, v43
	v_lshl_add_u64 v[34:35], v[34:35], 1, v[44:45]
	v_ashrrev_i32_e32 v0, 5, v0
	s_waitcnt lgkmcnt(0)
	global_store_dwordx4 v[34:35], v[38:41], off
	v_mad_u64_u32 v[34:35], s[12:13], v0, s2, v[42:43]
	v_add_u32_e32 v0, s10, v0
	ds_read_b128 v[34:37], v34
	v_ashrrev_i32_e32 v38, 31, v0
	v_mul_lo_u32 v40, s0, v38
	v_mul_lo_u32 v41, s1, v0
	v_mad_u64_u32 v[38:39], s[12:13], s0, v0, 0
	v_add_u32_e32 v0, 0x600, v43
	v_add3_u32 v39, v39, v40, v41
	v_ashrrev_i32_e32 v0, 5, v0
	v_lshl_add_u64 v[46:47], v[38:39], 1, v[44:45]
	v_mad_u64_u32 v[38:39], s[12:13], v0, s2, v[42:43]
	ds_read_b128 v[38:41], v38
	v_add_u32_e32 v0, s10, v0
	s_waitcnt lgkmcnt(1)
	global_store_dwordx4 v[46:47], v[34:37], off
	s_nop 1
	v_ashrrev_i32_e32 v34, 31, v0
	v_mul_lo_u32 v36, s0, v34
	v_mul_lo_u32 v37, s1, v0
	v_mad_u64_u32 v[34:35], s[12:13], s0, v0, 0
	v_add3_u32 v35, v35, v36, v37
	v_add_u32_e32 v0, 0x800, v43
	v_lshl_add_u64 v[34:35], v[34:35], 1, v[44:45]
	v_ashrrev_i32_e32 v0, 5, v0
	s_waitcnt lgkmcnt(0)
	global_store_dwordx4 v[34:35], v[38:41], off
	v_mad_u64_u32 v[34:35], s[12:13], v0, s2, v[42:43]
	v_add_u32_e32 v0, s10, v0
	ds_read_b128 v[34:37], v34
	v_ashrrev_i32_e32 v38, 31, v0
	v_mul_lo_u32 v40, s0, v38
	v_mul_lo_u32 v41, s1, v0
	v_mad_u64_u32 v[38:39], s[12:13], s0, v0, 0
	v_add_u32_e32 v0, 0xa00, v43
	v_add3_u32 v39, v39, v40, v41
	v_ashrrev_i32_e32 v0, 5, v0
	v_lshl_add_u64 v[46:47], v[38:39], 1, v[44:45]
	v_mad_u64_u32 v[38:39], s[12:13], v0, s2, v[42:43]
	ds_read_b128 v[38:41], v38
	v_add_u32_e32 v0, s10, v0
	s_waitcnt lgkmcnt(1)
	global_store_dwordx4 v[46:47], v[34:37], off
	s_nop 1
	v_ashrrev_i32_e32 v34, 31, v0
	v_mul_lo_u32 v36, s0, v34
	v_mul_lo_u32 v37, s1, v0
	v_mad_u64_u32 v[34:35], s[12:13], s0, v0, 0
	v_add3_u32 v35, v35, v36, v37
	v_add_u32_e32 v0, 0xc00, v43
	v_lshl_add_u64 v[34:35], v[34:35], 1, v[44:45]
	v_ashrrev_i32_e32 v0, 5, v0
	s_waitcnt lgkmcnt(0)
	global_store_dwordx4 v[34:35], v[38:41], off
	v_mad_u64_u32 v[34:35], s[12:13], v0, s2, v[42:43]
	v_add_u32_e32 v0, s10, v0
	ds_read_b128 v[34:37], v34
	v_ashrrev_i32_e32 v38, 31, v0
	v_mul_lo_u32 v40, s0, v38
	v_mul_lo_u32 v41, s1, v0
	v_mad_u64_u32 v[38:39], s[12:13], s0, v0, 0
	v_add_u32_e32 v0, 0xe00, v43
	v_add3_u32 v39, v39, v40, v41
	v_ashrrev_i32_e32 v0, 5, v0
	v_lshl_add_u64 v[46:47], v[38:39], 1, v[44:45]
	v_mad_u64_u32 v[38:39], s[12:13], v0, s2, v[42:43]
	ds_read_b128 v[38:41], v38
	v_add_u32_e32 v0, s10, v0
	s_waitcnt lgkmcnt(1)
	global_store_dwordx4 v[46:47], v[34:37], off
	s_nop 1
	v_ashrrev_i32_e32 v34, 31, v0
	v_mul_lo_u32 v36, s0, v34
	v_mul_lo_u32 v37, s1, v0
	v_mad_u64_u32 v[34:35], s[12:13], s0, v0, 0
	v_add3_u32 v35, v35, v36, v37
	v_add_u32_e32 v0, 0x1000, v43
	v_lshl_add_u64 v[34:35], v[34:35], 1, v[44:45]
	v_ashrrev_i32_e32 v0, 5, v0
	s_waitcnt lgkmcnt(0)
; #define RTID opaque_tid()
; __device__ __forceinline__ void phase_win(const Params& p, int part, u16* smem, volatile LAS unsigned* vb_) {
;     ...
;     const int tid2 = RTID;
; #pragma unroll
;     for (int k = 0; k < 16; ++k) {
;       const int c = tid2 + 512 * k;
;       const int row = c >> 5, ch = c & 31;
;       const uint4 v = *(const uint4*)(smem + row * 264 + ch * 8);
;       u16* d_ = (ch < 16) ? dstA : dstB;
;       const int l_ = (ch < 16) ? ldA : ldB;
;       *(uint4*)(d_ + (size_t)(mt * 256 + row) * l_ + (ch & 15) * 8) = v;
;     }
;     __syncthreads();
	global_store_dwordx4 v[34:35], v[38:41], off
	v_mad_u64_u32 v[34:35], s[12:13], v0, s2, v[42:43]
	v_add_u32_e32 v0, s10, v0
	ds_read_b128 v[34:37], v34
	v_ashrrev_i32_e32 v38, 31, v0
	v_mul_lo_u32 v40, s0, v38
	v_mul_lo_u32 v41, s1, v0
	v_mad_u64_u32 v[38:39], s[12:13], s0, v0, 0
	v_add_u32_e32 v0, 0x1200, v43
	v_add3_u32 v39, v39, v40, v41
	v_ashrrev_i32_e32 v0, 5, v0
	v_lshl_add_u64 v[46:47], v[38:39], 1, v[44:45]
	v_mad_u64_u32 v[38:39], s[12:13], v0, s2, v[42:43]
	ds_read_b128 v[38:41], v38
	v_add_u32_e32 v0, s10, v0
	s_waitcnt lgkmcnt(1)
	global_store_dwordx4 v[46:47], v[34:37], off
	s_nop 1
	v_ashrrev_i32_e32 v34, 31, v0
	v_mul_lo_u32 v36, s0, v34
	v_mul_lo_u32 v37, s1, v0
	v_mad_u64_u32 v[34:35], s[12:13], s0, v0, 0
	v_add3_u32 v35, v35, v36, v37
	v_add_u32_e32 v0, 0x1400, v43
	v_lshl_add_u64 v[34:35], v[34:35], 1, v[44:45]
	v_ashrrev_i32_e32 v0, 5, v0
	s_waitcnt lgkmcnt(0)
	global_store_dwordx4 v[34:35], v[38:41], off
	v_mad_u64_u32 v[34:35], s[12:13], v0, s2, v[42:43]
	v_add_u32_e32 v0, s10, v0
	ds_read_b128 v[34:37], v34
	v_ashrrev_i32_e32 v38, 31, v0
	v_mul_lo_u32 v40, s0, v38
	v_mul_lo_u32 v41, s1, v0
	v_mad_u64_u32 v[38:39], s[12:13], s0, v0, 0
	v_add_u32_e32 v0, 0x1600, v43
	v_add3_u32 v39, v39, v40, v41
	v_ashrrev_i32_e32 v0, 5, v0
	v_lshl_add_u64 v[46:47], v[38:39], 1, v[44:45]
	v_mad_u64_u32 v[38:39], s[12:13], v0, s2, v[42:43]
	ds_read_b128 v[38:41], v38
	v_add_u32_e32 v0, s10, v0
	s_waitcnt lgkmcnt(1)
	global_store_dwordx4 v[46:47], v[34:37], off
	s_nop 1
	v_ashrrev_i32_e32 v34, 31, v0
	v_mul_lo_u32 v36, s0, v34
	v_mul_lo_u32 v37, s1, v0
	v_mad_u64_u32 v[34:35], s[12:13], s0, v0, 0
	v_add3_u32 v35, v35, v36, v37
	v_add_u32_e32 v0, 0x1800, v43
	v_lshl_add_u64 v[34:35], v[34:35], 1, v[44:45]
	v_ashrrev_i32_e32 v0, 5, v0
	s_waitcnt lgkmcnt(0)
	global_store_dwordx4 v[34:35], v[38:41], off
	v_mad_u64_u32 v[34:35], s[12:13], v0, s2, v[42:43]
	v_add_u32_e32 v0, s10, v0
	ds_read_b128 v[34:37], v34
	v_ashrrev_i32_e32 v38, 31, v0
	v_mul_lo_u32 v40, s0, v38
	v_mul_lo_u32 v41, s1, v0
	v_mad_u64_u32 v[38:39], s[12:13], s0, v0, 0
	v_add_u32_e32 v0, 0x1a00, v43
	v_add3_u32 v39, v39, v40, v41
	v_ashrrev_i32_e32 v0, 5, v0
	v_lshl_add_u64 v[46:47], v[38:39], 1, v[44:45]
	v_mad_u64_u32 v[38:39], s[12:13], v0, s2, v[42:43]
	ds_read_b128 v[38:41], v38
	v_add_u32_e32 v0, s10, v0
	s_waitcnt lgkmcnt(1)
	global_store_dwordx4 v[46:47], v[34:37], off
	s_nop 1
	v_ashrrev_i32_e32 v34, 31, v0
	v_mul_lo_u32 v36, s0, v34
	v_mul_lo_u32 v37, s1, v0
	v_mad_u64_u32 v[34:35], s[12:13], s0, v0, 0
	v_add3_u32 v35, v35, v36, v37
	v_add_u32_e32 v0, 0x1c00, v43
	v_lshl_add_u64 v[34:35], v[34:35], 1, v[44:45]
	v_ashrrev_i32_e32 v0, 5, v0
	s_waitcnt lgkmcnt(0)
	global_store_dwordx4 v[34:35], v[38:41], off
	v_mad_u64_u32 v[34:35], s[12:13], v0, s2, v[42:43]
	v_add_u32_e32 v0, s10, v0
	ds_read_b128 v[34:37], v34
	v_ashrrev_i32_e32 v38, 31, v0
	v_mul_lo_u32 v40, s0, v38
	v_mul_lo_u32 v41, s1, v0
	v_mad_u64_u32 v[38:39], s[12:13], s0, v0, 0
	v_add_u32_e32 v0, 0x1e00, v43
	v_add3_u32 v39, v39, v40, v41
	v_ashrrev_i32_e32 v0, 5, v0
	v_lshl_add_u64 v[46:47], v[38:39], 1, v[44:45]
	v_mad_u64_u32 v[38:39], s[12:13], v0, s2, v[42:43]
	ds_read_b128 v[38:41], v38
	v_add_u32_e32 v0, s10, v0
	s_waitcnt lgkmcnt(1)
	global_store_dwordx4 v[46:47], v[34:37], off
	s_mov_b64 s[12:13], -1
	s_nop 0
	v_ashrrev_i32_e32 v34, 31, v0
	v_mul_lo_u32 v36, s0, v34
	v_mul_lo_u32 v37, s1, v0
	v_mad_u64_u32 v[34:35], s[0:1], s0, v0, 0
	v_add3_u32 v35, v35, v36, v37
	v_lshl_add_u64 v[34:35], v[34:35], 1, v[44:45]
	s_waitcnt lgkmcnt(0)
	global_store_dwordx4 v[34:35], v[38:41], off
	s_barrier
	s_cbranch_vccz .LBB0_441

; template <int MI, int NJ> ...
;     ...
;   for (int kt = 0; kt < nk; ++kt) {
;     const int buf = kt & 1;
;     {
;       G8STORE(buf ^ 1);
;       const u16* ga_ = (kt + 2 < nk) ? Ag + (kt + 2) * 64 : Ag + nAoff;
;       const u16* gb_ = (kt + 2 < nk) ? Bg + (kt + 2) * 64 : Bg + nBoff;
;       G8LOADP(ga_, gb_);
;     }
;     __builtin_amdgcn_sched_barrier(0);
;     __builtin_amdgcn_s_setprio(1);
;     const u16* a = ra_ + buf * AROWS * 64;
;     const u16* b = rb_ + buf * BROWS * 64;
; #pragma unroll
;     for (int ks = 0; ks < 2; ++ks) {
;       const u16* a_ = ks ? a + dsw : a;
;       const u16* b_ = ks ? b + dsw : b;
;       bf16x8 bfr[NJ];
; #pragma unroll
;       for (int j = 0; j < NJ; ++j) bfr[j] = *(const bf16x8*)(b_ + j * 16 * 64);
; #pragma unroll
;       for (int ih = 0; ih < MI / 4; ++ih) {
;         bf16x8 af[4];
; #pragma unroll
;         for (int i = 0; i < 4; ++i) af[i] = *(const bf16x8*)(a_ + (ih * 4 + i) * 16 * 64);
; #pragma unroll
;         for (int i = 0; i < 4; ++i)
; #pragma unroll
;           for (int j = 0; j < NJ; ++j) acc[ih * 4 + i][j] = mfma16(af[i], bfr[j], acc[ih * 4 + i][j]);
;       }
;     }
;     __builtin_amdgcn_s_setprio(0);
;     __builtin_amdgcn_sched_barrier(0);
;     __syncthreads();
;   }
.LBB0_481:
	s_and_b32 s45, s43, 0x4000
	s_xor_b32 s46, s45, 0x4000
	s_lshl_b32 s46, s46, 1
	v_add_u32_e32 v228, s46, v185
	v_add_u32_e32 v229, s46, v186
	s_add_i32 s46, s44, 2
	s_cmp_lt_u32 s46, s21
	s_cselect_b32 s47, 0, s12
	s_cselect_b32 s46, s39, s13
	s_cselect_b32 s49, 0, s37
	s_cselect_b32 s48, s39, s38
	s_lshl_b64 s[46:47], s[46:47], 1
	s_lshl_b64 s[48:49], s[48:49], 1
	s_add_u32 s50, s62, s46
	s_addc_u32 s51, s63, s47
	s_add_u32 s52, s64, s48
	s_addc_u32 s53, s65, s49
	s_setprio 1
	s_lshl_b32 s45, s45, 1
	v_add_u32_e32 v0, s45, v187
	v_add_u32_e32 v191, s45, v188
	ds_read_b128 v[166:169], v191
	ds_read_b128 v[162:165], v0
	ds_read_b128 v[170:173], v191 offset:2048
	ds_read_b128 v[192:195], v191 offset:4096
	ds_read_b128 v[196:199], v191 offset:6144
	ds_read_b128 v[204:207], v0 offset:2048
	ds_read_b128 v[208:211], v0 offset:4096
	v_add_u32_e32 v191, v191, v190
	s_waitcnt lgkmcnt(5)
	v_mfma_f32_16x16x32_bf16 v[158:161], v[166:169], v[162:165], v[158:161]
	s_waitcnt lgkmcnt(4)
	v_mfma_f32_16x16x32_bf16 v[154:157], v[170:173], v[162:165], v[154:157]
	s_waitcnt lgkmcnt(3)
	v_mfma_f32_16x16x32_bf16 v[150:153], v[192:195], v[162:165], v[150:153]
	s_waitcnt lgkmcnt(2)
	v_mfma_f32_16x16x32_bf16 v[146:149], v[196:199], v[162:165], v[146:149]
	ds_read_b128 v[162:165], v0 offset:6144
	s_waitcnt lgkmcnt(2)
	v_mfma_f32_16x16x32_bf16 v[142:145], v[166:169], v[204:207], v[142:145]
	v_mfma_f32_16x16x32_bf16 v[138:141], v[170:173], v[204:207], v[138:141]
	v_mfma_f32_16x16x32_bf16 v[134:137], v[192:195], v[204:207], v[134:137]
	v_mfma_f32_16x16x32_bf16 v[130:133], v[196:199], v[204:207], v[130:133]
	ds_read_b128 v[204:207], v0 offset:8192
	s_waitcnt vmcnt(7)
	ds_write_b128 v228, v[10:13]
	global_load_dwordx4 v[10:13], v234, s[50:51]
	s_waitcnt lgkmcnt(3)
	v_mfma_f32_16x16x32_bf16 v[126:129], v[166:169], v[208:211], v[126:129]
	v_mfma_f32_16x16x32_bf16 v[122:125], v[170:173], v[208:211], v[122:125]
	v_mfma_f32_16x16x32_bf16 v[118:121], v[192:195], v[208:211], v[118:121]
	v_mfma_f32_16x16x32_bf16 v[114:117], v[196:199], v[208:211], v[114:117]
	ds_read_b128 v[208:211], v0 offset:10240
	s_waitcnt vmcnt(7)
	ds_write_b128 v228, v[2:5] offset:8192
	global_load_dwordx4 v[2:5], v235, s[50:51]
	ds_read_b128 v[212:215], v191
	ds_read_b128 v[216:219], v191 offset:2048
	s_waitcnt lgkmcnt(6)
	v_mfma_f32_16x16x32_bf16 v[110:113], v[166:169], v[162:165], v[110:113]
	v_mfma_f32_16x16x32_bf16 v[106:109], v[170:173], v[162:165], v[106:109]
	v_mfma_f32_16x16x32_bf16 v[102:105], v[192:195], v[162:165], v[102:105]
	v_mfma_f32_16x16x32_bf16 v[98:101], v[196:199], v[162:165], v[98:101]
	ds_read_b128 v[162:165], v0 offset:12288
	s_waitcnt vmcnt(7)
	ds_write_b128 v228, v[6:9] offset:16384
	global_load_dwordx4 v[6:9], v236, s[50:51]
	ds_read_b128 v[220:223], v191 offset:4096
	ds_read_b128 v[224:227], v191 offset:6144
	s_waitcnt lgkmcnt(9)
	v_mfma_f32_16x16x32_bf16 v[94:97], v[166:169], v[204:207], v[94:97]
	v_mfma_f32_16x16x32_bf16 v[90:93], v[170:173], v[204:207], v[90:93]
	v_mfma_f32_16x16x32_bf16 v[86:89], v[192:195], v[204:207], v[86:89]
	v_mfma_f32_16x16x32_bf16 v[82:85], v[196:199], v[204:207], v[82:85]
	ds_read_b128 v[204:207], v0 offset:14336
	s_waitcnt vmcnt(7)
	ds_write_b128 v228, v[14:17] offset:24576
	global_load_dwordx4 v[14:17], v237, s[50:51]
	s_waitcnt lgkmcnt(9)
	v_mfma_f32_16x16x32_bf16 v[78:81], v[166:169], v[208:211], v[78:81]
	v_mfma_f32_16x16x32_bf16 v[70:73], v[170:173], v[208:211], v[70:73]
	v_mfma_f32_16x16x32_bf16 v[66:69], v[192:195], v[208:211], v[66:69]
	v_mfma_f32_16x16x32_bf16 v[58:61], v[196:199], v[208:211], v[58:61]
	v_add_u32_e32 v0, v0, v190
	ds_read_b128 v[208:211], v0
	s_waitcnt vmcnt(7)
	ds_write_b128 v229, v[18:21]
	global_load_dwordx4 v[18:21], v234, s[52:53]
	s_waitcnt lgkmcnt(7)
	v_mfma_f32_16x16x32_bf16 v[54:57], v[166:169], v[162:165], v[54:57]
	v_mfma_f32_16x16x32_bf16 v[50:53], v[170:173], v[162:165], v[50:53]
	v_mfma_f32_16x16x32_bf16 v[46:49], v[192:195], v[162:165], v[46:49]
	v_mfma_f32_16x16x32_bf16 v[38:41], v[196:199], v[162:165], v[38:41]
	ds_read_b128 v[162:165], v0 offset:2048
	s_waitcnt vmcnt(7)
	ds_write_b128 v229, v[42:45] offset:8192
	global_load_dwordx4 v[42:45], v235, s[52:53]
	s_waitcnt lgkmcnt(5)
	v_mfma_f32_16x16x32_bf16 v[34:37], v[166:169], v[204:207], v[34:37]
	v_mfma_f32_16x16x32_bf16 v[30:33], v[170:173], v[204:207], v[30:33]
	v_mfma_f32_16x16x32_bf16 v[26:29], v[192:195], v[204:207], v[26:29]
	v_mfma_f32_16x16x32_bf16 v[22:25], v[196:199], v[204:207], v[22:25]
	ds_read_b128 v[204:207], v0 offset:4096
	s_waitcnt vmcnt(7)
	ds_write_b128 v229, v[62:65] offset:16384
	global_load_dwordx4 v[62:65], v236, s[52:53]
	s_waitcnt lgkmcnt(5)
	v_mfma_f32_16x16x32_bf16 v[158:161], v[212:215], v[208:211], v[158:161]
	v_mfma_f32_16x16x32_bf16 v[154:157], v[216:219], v[208:211], v[154:157]
	v_mfma_f32_16x16x32_bf16 v[150:153], v[220:223], v[208:211], v[150:153]
	v_mfma_f32_16x16x32_bf16 v[146:149], v[224:227], v[208:211], v[146:149]
	ds_read_b128 v[208:211], v0 offset:6144
	s_waitcnt vmcnt(7)
	ds_write_b128 v229, v[74:77] offset:24576
	global_load_dwordx4 v[74:77], v237, s[52:53]
	s_waitcnt lgkmcnt(5)
	v_mfma_f32_16x16x32_bf16 v[142:145], v[212:215], v[162:165], v[142:145]
	v_mfma_f32_16x16x32_bf16 v[138:141], v[216:219], v[162:165], v[138:141]
	v_mfma_f32_16x16x32_bf16 v[134:137], v[220:223], v[162:165], v[134:137]
	v_mfma_f32_16x16x32_bf16 v[130:133], v[224:227], v[162:165], v[130:133]
	ds_read_b128 v[162:165], v0 offset:8192
	s_waitcnt lgkmcnt(4)
; template <int MI, int NJ> ...
;     ...
; #pragma unroll
;     for (int ks = 0; ks < 2; ++ks) {
;       const u16* a_ = ks ? a + dsw : a;
;       const u16* b_ = ks ? b + dsw : b;
;       bf16x8 bfr[NJ];
; #pragma unroll
;       for (int j = 0; j < NJ; ++j) bfr[j] = *(const bf16x8*)(b_ + j * 16 * 64);
; #pragma unroll
;       for (int ih = 0; ih < MI / 4; ++ih) {
;         bf16x8 af[4];
; #pragma unroll
;         for (int i = 0; i < 4; ++i) af[i] = *(const bf16x8*)(a_ + (ih * 4 + i) * 16 * 64);
; #pragma unroll
;         for (int i = 0; i < 4; ++i)
; #pragma unroll
;           for (int j = 0; j < NJ; ++j) acc[ih * 4 + i][j] = mfma16(af[i], bfr[j], acc[ih * 4 + i][j]);
;       }
;     }
;     __builtin_amdgcn_s_setprio(0);
;     __builtin_amdgcn_sched_barrier(0);
;     __syncthreads();
;   }
; __device__ __forceinline__ void phase_gemm_f32(const u16* A, const u16* Bt, int K, u16* out, u16* smem,
;                                                volatile LAS unsigned* vb_) {
;     ...
; #pragma unroll
;     for (int i = 0; i < 8; ++i)
; #pragma unroll
;       for (int j = 0; j < 4; ++j)
; #pragma unroll
;         for (int r = 0; r < 4; ++r)
;           smem[(wm * 128 + i * 16 + (lane >> 4) * 4 + r) * 264 + wn * 64 + j * 16 + (lane & 15)] = f2bf(acc[i][j][r]);
;     __syncthreads();
	v_mfma_f32_16x16x32_bf16 v[126:129], v[212:215], v[204:207], v[126:129]
	v_mfma_f32_16x16x32_bf16 v[122:125], v[216:219], v[204:207], v[122:125]
	v_mfma_f32_16x16x32_bf16 v[118:121], v[220:223], v[204:207], v[118:121]
	v_mfma_f32_16x16x32_bf16 v[114:117], v[224:227], v[204:207], v[114:117]
	ds_read_b128 v[204:207], v0 offset:10240
	s_waitcnt lgkmcnt(3)
	v_mfma_f32_16x16x32_bf16 v[110:113], v[212:215], v[208:211], v[110:113]
	v_mfma_f32_16x16x32_bf16 v[106:109], v[216:219], v[208:211], v[106:109]
	v_mfma_f32_16x16x32_bf16 v[102:105], v[220:223], v[208:211], v[102:105]
	v_mfma_f32_16x16x32_bf16 v[98:101], v[224:227], v[208:211], v[98:101]
	ds_read_b128 v[208:211], v0 offset:12288
	s_waitcnt lgkmcnt(2)
	v_mfma_f32_16x16x32_bf16 v[94:97], v[212:215], v[162:165], v[94:97]
	v_mfma_f32_16x16x32_bf16 v[90:93], v[216:219], v[162:165], v[90:93]
	v_mfma_f32_16x16x32_bf16 v[86:89], v[220:223], v[162:165], v[86:89]
	v_mfma_f32_16x16x32_bf16 v[82:85], v[224:227], v[162:165], v[82:85]
	ds_read_b128 v[162:165], v0 offset:14336
	s_waitcnt lgkmcnt(2)
	v_mfma_f32_16x16x32_bf16 v[78:81], v[212:215], v[204:207], v[78:81]
	v_mfma_f32_16x16x32_bf16 v[70:73], v[216:219], v[204:207], v[70:73]
	v_mfma_f32_16x16x32_bf16 v[66:69], v[220:223], v[204:207], v[66:69]
	v_mfma_f32_16x16x32_bf16 v[58:61], v[224:227], v[204:207], v[58:61]
	s_waitcnt lgkmcnt(1)
	v_mfma_f32_16x16x32_bf16 v[54:57], v[212:215], v[208:211], v[54:57]
	v_mfma_f32_16x16x32_bf16 v[50:53], v[216:219], v[208:211], v[50:53]
	v_mfma_f32_16x16x32_bf16 v[46:49], v[220:223], v[208:211], v[46:49]
	v_mfma_f32_16x16x32_bf16 v[38:41], v[224:227], v[208:211], v[38:41]
	s_waitcnt lgkmcnt(0)
	v_mfma_f32_16x16x32_bf16 v[34:37], v[212:215], v[162:165], v[34:37]
	v_mfma_f32_16x16x32_bf16 v[30:33], v[216:219], v[162:165], v[30:33]
	v_mfma_f32_16x16x32_bf16 v[26:29], v[220:223], v[162:165], v[26:29]
	v_mfma_f32_16x16x32_bf16 v[22:25], v[224:227], v[162:165], v[22:25]
	s_setprio 0
	s_add_i32 s44, s44, 1
	s_add_i32 s39, s39, 64
	s_addk_i32 s43, 0x4000
	s_cmp_lg_u32 s21, s44
	s_barrier
	s_cbranch_scc1 .LBB0_481
	v_and_b32_e32 v228, 15, v175
	v_bfe_u32 v229, v175, 8, 1
	v_lshl_or_b32 v228, v229, 7, v228
	v_mul_u32_u24_e32 v228, 0x210, v228
	v_bfe_u32 v229, v175, 6, 2
	v_lshl_add_u32 v228, v229, 7, v228
	v_bfe_u32 v229, v175, 4, 2
	v_lshl_add_u32 v228, v229, 3, v228
	v_cvt_pk_bf16_f32 v158, v158, v159
	v_cvt_pk_bf16_f32 v159, v160, v161
	v_cvt_pk_bf16_f32 v154, v154, v155
	v_cvt_pk_bf16_f32 v155, v156, v157
	v_cvt_pk_bf16_f32 v150, v150, v151
	v_cvt_pk_bf16_f32 v151, v152, v153
	v_cvt_pk_bf16_f32 v146, v146, v147
	v_cvt_pk_bf16_f32 v147, v148, v149
	ds_write_b64 v228, v[158:159]
	ds_write_b64 v228, v[154:155] offset:32
	ds_write_b64 v228, v[150:151] offset:64
	ds_write_b64 v228, v[146:147] offset:96
	v_cvt_pk_bf16_f32 v142, v142, v143
	v_cvt_pk_bf16_f32 v143, v144, v145
	v_cvt_pk_bf16_f32 v138, v138, v139
	v_cvt_pk_bf16_f32 v139, v140, v141
	v_cvt_pk_bf16_f32 v134, v134, v135
	v_cvt_pk_bf16_f32 v135, v136, v137
	v_cvt_pk_bf16_f32 v130, v130, v131
	v_cvt_pk_bf16_f32 v131, v132, v133
	ds_write_b64 v228, v[142:143] offset:8448
	ds_write_b64 v228, v[138:139] offset:8480
	ds_write_b64 v228, v[134:135] offset:8512
	ds_write_b64 v228, v[130:131] offset:8544
	v_cvt_pk_bf16_f32 v126, v126, v127
	v_cvt_pk_bf16_f32 v127, v128, v129
	v_cvt_pk_bf16_f32 v122, v122, v123
	v_cvt_pk_bf16_f32 v123, v124, v125
	v_cvt_pk_bf16_f32 v118, v118, v119
	v_cvt_pk_bf16_f32 v119, v120, v121
	v_cvt_pk_bf16_f32 v114, v114, v115
	v_cvt_pk_bf16_f32 v115, v116, v117
	ds_write_b64 v228, v[126:127] offset:16896
	ds_write_b64 v228, v[122:123] offset:16928
	ds_write_b64 v228, v[118:119] offset:16960
	ds_write_b64 v228, v[114:115] offset:16992
	v_cvt_pk_bf16_f32 v110, v110, v111
	v_cvt_pk_bf16_f32 v111, v112, v113
	v_cvt_pk_bf16_f32 v106, v106, v107
	v_cvt_pk_bf16_f32 v107, v108, v109
	v_cvt_pk_bf16_f32 v102, v102, v103
	v_cvt_pk_bf16_f32 v103, v104, v105
	v_cvt_pk_bf16_f32 v98, v98, v99
	v_cvt_pk_bf16_f32 v99, v100, v101
	ds_write_b64 v228, v[110:111] offset:25344
	ds_write_b64 v228, v[106:107] offset:25376
	ds_write_b64 v228, v[102:103] offset:25408
	ds_write_b64 v228, v[98:99] offset:25440
	v_cvt_pk_bf16_f32 v94, v94, v95
	v_cvt_pk_bf16_f32 v95, v96, v97
	v_cvt_pk_bf16_f32 v90, v90, v91
	v_cvt_pk_bf16_f32 v91, v92, v93
	v_cvt_pk_bf16_f32 v86, v86, v87
	v_cvt_pk_bf16_f32 v87, v88, v89
	v_cvt_pk_bf16_f32 v82, v82, v83
	v_cvt_pk_bf16_f32 v83, v84, v85
	ds_write_b64 v228, v[94:95] offset:33792
	ds_write_b64 v228, v[90:91] offset:33824
	ds_write_b64 v228, v[86:87] offset:33856
	ds_write_b64 v228, v[82:83] offset:33888
	v_cvt_pk_bf16_f32 v78, v78, v79
	v_cvt_pk_bf16_f32 v79, v80, v81
	v_cvt_pk_bf16_f32 v70, v70, v71
	v_cvt_pk_bf16_f32 v71, v72, v73
	v_cvt_pk_bf16_f32 v66, v66, v67
	v_cvt_pk_bf16_f32 v67, v68, v69
	v_cvt_pk_bf16_f32 v58, v58, v59
	v_cvt_pk_bf16_f32 v59, v60, v61
	ds_write_b64 v228, v[78:79] offset:42240
	ds_write_b64 v228, v[70:71] offset:42272
	ds_write_b64 v228, v[66:67] offset:42304
	ds_write_b64 v228, v[58:59] offset:42336
	v_cvt_pk_bf16_f32 v54, v54, v55
	v_cvt_pk_bf16_f32 v55, v56, v57
	v_cvt_pk_bf16_f32 v50, v50, v51
	v_cvt_pk_bf16_f32 v51, v52, v53
	v_cvt_pk_bf16_f32 v46, v46, v47
	v_cvt_pk_bf16_f32 v47, v48, v49
	v_cvt_pk_bf16_f32 v38, v38, v39
	v_cvt_pk_bf16_f32 v39, v40, v41
	ds_write_b64 v228, v[54:55] offset:50688
	ds_write_b64 v228, v[50:51] offset:50720
	ds_write_b64 v228, v[46:47] offset:50752
	ds_write_b64 v228, v[38:39] offset:50784
	v_cvt_pk_bf16_f32 v34, v34, v35
	v_cvt_pk_bf16_f32 v35, v36, v37
	v_cvt_pk_bf16_f32 v30, v30, v31
	v_cvt_pk_bf16_f32 v31, v32, v33
	v_cvt_pk_bf16_f32 v26, v26, v27
	v_cvt_pk_bf16_f32 v27, v28, v29
	v_cvt_pk_bf16_f32 v22, v22, v23
	v_cvt_pk_bf16_f32 v23, v24, v25
	ds_write_b64 v228, v[34:35] offset:59136
	ds_write_b64 v228, v[30:31] offset:59168
	ds_write_b64 v228, v[26:27] offset:59200
	ds_write_b64 v228, v[22:23] offset:59232
	s_ashr_i32 s43, s42, 31
	v_mov_b32_e32 v34, v175
	s_lshl_b64 s[12:13], s[42:43], 1
	s_waitcnt lgkmcnt(0)
	s_barrier
; #define RTID opaque_tid()
; __device__ __forceinline__ void phase_gemm_f32(const u16* A, const u16* Bt, int K, u16* out, u16* smem,
;                                                volatile LAS unsigned* vb_) {
;     ...
;     const int tid2 = RTID;
; #pragma unroll
;     for (int k = 0; k < 16; ++k) {
;       const int c = tid2 + 512 * k;
;       const int row = c >> 5, ch = c & 31;
;       const uint4 v = *(const uint4*)(smem + row * 264 + ch * 8);
;       *(uint4*)(out + (size_t)(mt * 256 + row) * 1024 + nt * 256 + ch * 8) = v;
;     }
;     __syncthreads();
	s_add_u32 s12, s11, s12
	v_lshlrev_b32_e32 v0, 4, v34
	v_and_b32_e32 v0, 0x1f0, v0
	s_addc_u32 s13, s20, s13
	v_ashrrev_i32_e32 v26, 5, v34
	v_lshl_add_u64 v[30:31], s[12:13], 0, v[0:1]
	v_mad_u64_u32 v[22:23], s[12:13], v26, s2, v[0:1]
	v_add_u32_e32 v26, s23, v26
	v_ashrrev_i32_e32 v27, 31, v26
	ds_read_b128 v[22:25], v22
	v_lshlrev_b64 v[26:27], 11, v[26:27]
	v_lshl_add_u64 v[32:33], v[30:31], 0, v[26:27]
	v_add_u32_e32 v26, 0x200, v34
	v_ashrrev_i32_e32 v35, 5, v26
	v_mad_u64_u32 v[26:27], s[12:13], v35, s2, v[0:1]
	ds_read_b128 v[26:29], v26
	s_waitcnt lgkmcnt(1)
	global_store_dwordx4 v[32:33], v[22:25], off
	s_and_b64 vcc, exec, s[40:41]
	s_mov_b32 s37, s36
	v_add_u32_e32 v22, s23, v35
	v_ashrrev_i32_e32 v23, 31, v22
	v_lshlrev_b64 v[22:23], 11, v[22:23]
	v_lshl_add_u64 v[22:23], v[30:31], 0, v[22:23]
	s_waitcnt lgkmcnt(0)
	global_store_dwordx4 v[22:23], v[26:29], off
	v_add_u32_e32 v22, 0x400, v34
	s_nop 0
	v_ashrrev_i32_e32 v26, 5, v22
	v_mad_u64_u32 v[22:23], s[12:13], v26, s2, v[0:1]
	v_add_u32_e32 v26, s23, v26
	v_ashrrev_i32_e32 v27, 31, v26
	ds_read_b128 v[22:25], v22
	v_lshlrev_b64 v[26:27], 11, v[26:27]
	v_lshl_add_u64 v[32:33], v[30:31], 0, v[26:27]
	v_add_u32_e32 v26, 0x600, v34
	v_ashrrev_i32_e32 v35, 5, v26
	v_mad_u64_u32 v[26:27], s[12:13], v35, s2, v[0:1]
	ds_read_b128 v[26:29], v26
	s_waitcnt lgkmcnt(1)
	global_store_dwordx4 v[32:33], v[22:25], off
	s_nop 1
	v_add_u32_e32 v22, s23, v35
	v_ashrrev_i32_e32 v23, 31, v22
	v_lshlrev_b64 v[22:23], 11, v[22:23]
	v_lshl_add_u64 v[22:23], v[30:31], 0, v[22:23]
	s_waitcnt lgkmcnt(0)
	global_store_dwordx4 v[22:23], v[26:29], off
	v_add_u32_e32 v22, 0x800, v34
	s_nop 0
	v_ashrrev_i32_e32 v26, 5, v22
	v_mad_u64_u32 v[22:23], s[12:13], v26, s2, v[0:1]
	v_add_u32_e32 v26, s23, v26
	v_ashrrev_i32_e32 v27, 31, v26
	ds_read_b128 v[22:25], v22
	v_lshlrev_b64 v[26:27], 11, v[26:27]
	v_lshl_add_u64 v[32:33], v[30:31], 0, v[26:27]
	v_add_u32_e32 v26, 0xa00, v34
	v_ashrrev_i32_e32 v35, 5, v26
	v_mad_u64_u32 v[26:27], s[12:13], v35, s2, v[0:1]
	ds_read_b128 v[26:29], v26
	s_waitcnt lgkmcnt(1)
	global_store_dwordx4 v[32:33], v[22:25], off
	s_nop 1
	v_add_u32_e32 v22, s23, v35
	v_ashrrev_i32_e32 v23, 31, v22
	v_lshlrev_b64 v[22:23], 11, v[22:23]
	v_lshl_add_u64 v[22:23], v[30:31], 0, v[22:23]
	s_waitcnt lgkmcnt(0)
	global_store_dwordx4 v[22:23], v[26:29], off
	v_add_u32_e32 v22, 0xc00, v34
	s_nop 0
	v_ashrrev_i32_e32 v26, 5, v22
	v_mad_u64_u32 v[22:23], s[12:13], v26, s2, v[0:1]
	v_add_u32_e32 v26, s23, v26
	v_ashrrev_i32_e32 v27, 31, v26
	ds_read_b128 v[22:25], v22
	v_lshlrev_b64 v[26:27], 11, v[26:27]
	v_lshl_add_u64 v[32:33], v[30:31], 0, v[26:27]
	v_add_u32_e32 v26, 0xe00, v34
	v_ashrrev_i32_e32 v35, 5, v26
	v_mad_u64_u32 v[26:27], s[12:13], v35, s2, v[0:1]
	ds_read_b128 v[26:29], v26
	s_waitcnt lgkmcnt(1)
	global_store_dwordx4 v[32:33], v[22:25], off
	s_nop 1
	v_add_u32_e32 v22, s23, v35
	v_ashrrev_i32_e32 v23, 31, v22
	v_lshlrev_b64 v[22:23], 11, v[22:23]
	v_lshl_add_u64 v[22:23], v[30:31], 0, v[22:23]
	s_waitcnt lgkmcnt(0)
	global_store_dwordx4 v[22:23], v[26:29], off
	v_add_u32_e32 v22, 0x1000, v34
	s_nop 0
	v_ashrrev_i32_e32 v26, 5, v22
	v_mad_u64_u32 v[22:23], s[12:13], v26, s2, v[0:1]
	v_add_u32_e32 v26, s23, v26
	v_ashrrev_i32_e32 v27, 31, v26
	ds_read_b128 v[22:25], v22
	v_lshlrev_b64 v[26:27], 11, v[26:27]
	v_lshl_add_u64 v[32:33], v[30:31], 0, v[26:27]
	v_add_u32_e32 v26, 0x1200, v34
	v_ashrrev_i32_e32 v35, 5, v26
	v_mad_u64_u32 v[26:27], s[12:13], v35, s2, v[0:1]
	ds_read_b128 v[26:29], v26
	s_waitcnt lgkmcnt(1)
	global_store_dwordx4 v[32:33], v[22:25], off
	s_nop 1
	v_add_u32_e32 v22, s23, v35
	v_ashrrev_i32_e32 v23, 31, v22
	v_lshlrev_b64 v[22:23], 11, v[22:23]
	v_lshl_add_u64 v[22:23], v[30:31], 0, v[22:23]
	s_waitcnt lgkmcnt(0)
	global_store_dwordx4 v[22:23], v[26:29], off
	v_add_u32_e32 v22, 0x1400, v34
	s_nop 0
	v_ashrrev_i32_e32 v26, 5, v22
	v_mad_u64_u32 v[22:23], s[12:13], v26, s2, v[0:1]
	v_add_u32_e32 v26, s23, v26
	v_ashrrev_i32_e32 v27, 31, v26
	ds_read_b128 v[22:25], v22
	v_lshlrev_b64 v[26:27], 11, v[26:27]
	v_lshl_add_u64 v[32:33], v[30:31], 0, v[26:27]
	v_add_u32_e32 v26, 0x1600, v34
	v_ashrrev_i32_e32 v35, 5, v26
	v_mad_u64_u32 v[26:27], s[12:13], v35, s2, v[0:1]
	ds_read_b128 v[26:29], v26
	s_waitcnt lgkmcnt(1)
	global_store_dwordx4 v[32:33], v[22:25], off
	s_nop 1
	v_add_u32_e32 v22, s23, v35
	v_ashrrev_i32_e32 v23, 31, v22
	v_lshlrev_b64 v[22:23], 11, v[22:23]
	v_lshl_add_u64 v[22:23], v[30:31], 0, v[22:23]
	s_waitcnt lgkmcnt(0)
	global_store_dwordx4 v[22:23], v[26:29], off
	v_add_u32_e32 v22, 0x1800, v34
	s_nop 0
	v_ashrrev_i32_e32 v26, 5, v22
	v_mad_u64_u32 v[22:23], s[12:13], v26, s2, v[0:1]
	v_add_u32_e32 v26, s23, v26
	v_ashrrev_i32_e32 v27, 31, v26
	ds_read_b128 v[22:25], v22
	v_lshlrev_b64 v[26:27], 11, v[26:27]
	v_lshl_add_u64 v[32:33], v[30:31], 0, v[26:27]
	v_add_u32_e32 v26, 0x1a00, v34
	v_ashrrev_i32_e32 v35, 5, v26
	v_mad_u64_u32 v[26:27], s[12:13], v35, s2, v[0:1]
	ds_read_b128 v[26:29], v26
	s_waitcnt lgkmcnt(1)
	global_store_dwordx4 v[32:33], v[22:25], off
	s_nop 1
	v_add_u32_e32 v22, s23, v35
	v_ashrrev_i32_e32 v23, 31, v22
	v_lshlrev_b64 v[22:23], 11, v[22:23]
	v_lshl_add_u64 v[22:23], v[30:31], 0, v[22:23]
	s_waitcnt lgkmcnt(0)
	global_store_dwordx4 v[22:23], v[26:29], off
	v_add_u32_e32 v22, 0x1c00, v34
	s_nop 0
	v_ashrrev_i32_e32 v26, 5, v22
	v_mad_u64_u32 v[22:23], s[12:13], v26, s2, v[0:1]
	v_add_u32_e32 v26, s23, v26
	v_ashrrev_i32_e32 v27, 31, v26
	ds_read_b128 v[22:25], v22
	v_lshlrev_b64 v[26:27], 11, v[26:27]
	v_lshl_add_u64 v[32:33], v[30:31], 0, v[26:27]
	v_add_u32_e32 v26, 0x1e00, v34
	v_ashrrev_i32_e32 v34, 5, v26
	v_mad_u64_u32 v[26:27], s[12:13], v34, s2, v[0:1]
	ds_read_b128 v[26:29], v26
	s_waitcnt lgkmcnt(1)
	global_store_dwordx4 v[32:33], v[22:25], off
	s_mov_b64 s[12:13], -1
	s_nop 0
	v_add_u32_e32 v22, s23, v34
	v_ashrrev_i32_e32 v23, 31, v22
	v_lshlrev_b64 v[22:23], 11, v[22:23]
	v_lshl_add_u64 v[22:23], v[30:31], 0, v[22:23]
	s_waitcnt lgkmcnt(0)
	global_store_dwordx4 v[22:23], v[26:29], off
	s_barrier
	s_cbranch_vccz .LBB0_478

; template <int MI, int NJ> ...
;     ...
;   for (int kt = 0; kt < nk; ++kt) {
;     const int buf = kt & 1;
;     {
;       G8STORE(buf ^ 1);
;       const u16* ga_ = (kt + 2 < nk) ? Ag + (kt + 2) * 64 : Ag + nAoff;
;       const u16* gb_ = (kt + 2 < nk) ? Bg + (kt + 2) * 64 : Bg + nBoff;
;       G8LOADP(ga_, gb_);
;     }
;     __builtin_amdgcn_sched_barrier(0);
;     __builtin_amdgcn_s_setprio(1);
;     const u16* a = ra_ + buf * AROWS * 64;
;     const u16* b = rb_ + buf * BROWS * 64;
; #pragma unroll
;     for (int ks = 0; ks < 2; ++ks) {
;       const u16* a_ = ks ? a + dsw : a;
;       const u16* b_ = ks ? b + dsw : b;
;       bf16x8 bfr[NJ];
; #pragma unroll
;       for (int j = 0; j < NJ; ++j) bfr[j] = *(const bf16x8*)(b_ + j * 16 * 64);
; #pragma unroll
;       for (int ih = 0; ih < MI / 4; ++ih) {
;         bf16x8 af[4];
; #pragma unroll
;         for (int i = 0; i < 4; ++i) af[i] = *(const bf16x8*)(a_ + (ih * 4 + i) * 16 * 64);
; #pragma unroll
;         for (int i = 0; i < 4; ++i)
; #pragma unroll
;           for (int j = 0; j < NJ; ++j) acc[ih * 4 + i][j] = mfma16(af[i], bfr[j], acc[ih * 4 + i][j]);
;       }
;     }
;     __builtin_amdgcn_s_setprio(0);
;     __builtin_amdgcn_sched_barrier(0);
;     __syncthreads();
;   }
.LBB0_601:
	s_and_b32 s48, s42, 0x4000
	s_xor_b32 s44, s48, 0x4000
	s_lshl_b32 s44, s44, 1
	v_add_u32_e32 v170, s44, v185
	v_add_u32_e32 v171, s44, v186
	s_cmp_lt_u32 s43, 14
	s_cselect_b32 s45, s23, s13
	s_cselect_b32 s44, s22, s12
	s_cselect_b32 s47, s23, s21
	s_cselect_b32 s46, s22, s20
	s_lshl_b64 s[44:45], s[44:45], 1
	s_lshl_b64 s[46:47], s[46:47], 1
	s_add_u32 s50, s62, s44
	s_addc_u32 s51, s63, s45
	s_add_u32 s52, s64, s46
	s_addc_u32 s53, s65, s47
	s_setprio 1
	s_lshl_b32 s44, s48, 1
	v_add_u32_e32 v228, s44, v187
	v_add_u32_e32 v229, s44, v188
	ds_read_b128 v[212:215], v229
	ds_read_b128 v[208:211], v228
	ds_read_b128 v[216:219], v229 offset:2048
	ds_read_b128 v[220:223], v229 offset:4096
	ds_read_b128 v[224:227], v229 offset:6144
	ds_read_b128 v[234:237], v228 offset:2048
	ds_read_b128 v[238:241], v228 offset:4096
	v_add_u32_e32 v229, v229, v196
	s_waitcnt lgkmcnt(5)
	v_mfma_f32_16x16x32_bf16 v[158:161], v[212:215], v[208:211], v[158:161]
	s_waitcnt lgkmcnt(4)
	v_mfma_f32_16x16x32_bf16 v[154:157], v[216:219], v[208:211], v[154:157]
	s_waitcnt lgkmcnt(3)
	v_mfma_f32_16x16x32_bf16 v[150:153], v[220:223], v[208:211], v[150:153]
	s_waitcnt lgkmcnt(2)
	v_mfma_f32_16x16x32_bf16 v[146:149], v[224:227], v[208:211], v[146:149]
	ds_read_b128 v[208:211], v228 offset:6144
	s_waitcnt lgkmcnt(2)
	v_mfma_f32_16x16x32_bf16 v[142:145], v[212:215], v[234:237], v[142:145]
	v_mfma_f32_16x16x32_bf16 v[138:141], v[216:219], v[234:237], v[138:141]
	v_mfma_f32_16x16x32_bf16 v[134:137], v[220:223], v[234:237], v[134:137]
	v_mfma_f32_16x16x32_bf16 v[130:133], v[224:227], v[234:237], v[130:133]
	ds_read_b128 v[234:237], v228 offset:8192
	s_waitcnt vmcnt(7)
	ds_write_b128 v170, v[2:5]
	global_load_dwordx4 v[2:5], v250, s[50:51]
	s_waitcnt lgkmcnt(3)
	v_mfma_f32_16x16x32_bf16 v[126:129], v[212:215], v[238:241], v[126:129]
	v_mfma_f32_16x16x32_bf16 v[122:125], v[216:219], v[238:241], v[122:125]
	v_mfma_f32_16x16x32_bf16 v[118:121], v[220:223], v[238:241], v[118:121]
	v_mfma_f32_16x16x32_bf16 v[114:117], v[224:227], v[238:241], v[114:117]
	ds_read_b128 v[238:241], v228 offset:10240
	s_waitcnt vmcnt(7)
	ds_write_b128 v170, v[6:9] offset:8192
	global_load_dwordx4 v[6:9], v251, s[50:51]
	ds_read_b128 v[242:245], v229
	s_waitcnt lgkmcnt(5)
	v_mfma_f32_16x16x32_bf16 v[110:113], v[212:215], v[208:211], v[110:113]
	v_mfma_f32_16x16x32_bf16 v[106:109], v[216:219], v[208:211], v[106:109]
	v_mfma_f32_16x16x32_bf16 v[102:105], v[220:223], v[208:211], v[102:105]
	v_mfma_f32_16x16x32_bf16 v[98:101], v[224:227], v[208:211], v[98:101]
	ds_read_b128 v[208:211], v228 offset:12288
	s_waitcnt vmcnt(7)
	ds_write_b128 v170, v[10:13] offset:16384
	global_load_dwordx4 v[10:13], v172, s[50:51]
	ds_read_b128 v[246:249], v229 offset:2048
	s_waitcnt lgkmcnt(7)
	v_mfma_f32_16x16x32_bf16 v[94:97], v[212:215], v[234:237], v[94:97]
	v_mfma_f32_16x16x32_bf16 v[90:93], v[216:219], v[234:237], v[90:93]
	v_mfma_f32_16x16x32_bf16 v[86:89], v[220:223], v[234:237], v[86:89]
	v_mfma_f32_16x16x32_bf16 v[82:85], v[224:227], v[234:237], v[82:85]
	ds_read_b128 v[234:237], v228 offset:14336
	s_waitcnt vmcnt(7)
	ds_write_b128 v170, v[18:21] offset:24576
	global_load_dwordx4 v[18:21], v173, s[50:51]
	s_waitcnt lgkmcnt(7)
	v_mfma_f32_16x16x32_bf16 v[78:81], v[212:215], v[238:241], v[78:81]
	v_mfma_f32_16x16x32_bf16 v[74:77], v[216:219], v[238:241], v[74:77]
	v_mfma_f32_16x16x32_bf16 v[70:73], v[220:223], v[238:241], v[70:73]
	v_mfma_f32_16x16x32_bf16 v[66:69], v[224:227], v[238:241], v[66:69]
	v_add_u32_e32 v228, v228, v196
	ds_read_b128 v[238:241], v228
	s_waitcnt vmcnt(7)
	ds_write_b128 v171, v[14:17]
	global_load_dwordx4 v[14:17], v250, s[52:53]
	s_waitcnt lgkmcnt(6)
	v_mfma_f32_16x16x32_bf16 v[62:65], v[212:215], v[208:211], v[62:65]
	v_mfma_f32_16x16x32_bf16 v[58:61], v[216:219], v[208:211], v[58:61]
	v_mfma_f32_16x16x32_bf16 v[54:57], v[220:223], v[208:211], v[54:57]
	v_mfma_f32_16x16x32_bf16 v[50:53], v[224:227], v[208:211], v[50:53]
	ds_read_b128 v[208:211], v228 offset:2048
	s_waitcnt vmcnt(7)
	ds_write_b128 v171, v[22:25] offset:8192
	global_load_dwordx4 v[22:25], v251, s[52:53]
	s_waitcnt lgkmcnt(5)
	v_mfma_f32_16x16x32_bf16 v[38:41], v[220:223], v[234:237], v[38:41]
	v_mfma_f32_16x16x32_bf16 v[34:37], v[224:227], v[234:237], v[34:37]
	ds_read_b128 v[220:223], v229 offset:4096
	ds_read_b128 v[224:227], v229 offset:6144
	v_mfma_f32_16x16x32_bf16 v[46:49], v[212:215], v[234:237], v[46:49]
	v_mfma_f32_16x16x32_bf16 v[42:45], v[216:219], v[234:237], v[42:45]
	ds_read_b128 v[234:237], v228 offset:4096
	s_waitcnt vmcnt(7)
	ds_write_b128 v171, v[26:29] offset:16384
	global_load_dwordx4 v[26:29], v172, s[52:53]
	s_waitcnt lgkmcnt(7)
	v_mfma_f32_16x16x32_bf16 v[158:161], v[242:245], v[238:241], v[158:161]
	v_mfma_f32_16x16x32_bf16 v[154:157], v[246:249], v[238:241], v[154:157]
	s_waitcnt lgkmcnt(2)
	v_mfma_f32_16x16x32_bf16 v[150:153], v[220:223], v[238:241], v[150:153]
	v_mfma_f32_16x16x32_bf16 v[146:149], v[224:227], v[238:241], v[146:149]
	ds_read_b128 v[238:241], v228 offset:6144
	s_waitcnt vmcnt(7)
	ds_write_b128 v171, v[30:33] offset:24576
	global_load_dwordx4 v[30:33], v173, s[52:53]
	s_waitcnt lgkmcnt(7)
	v_mfma_f32_16x16x32_bf16 v[142:145], v[242:245], v[208:211], v[142:145]
	v_mfma_f32_16x16x32_bf16 v[138:141], v[246:249], v[208:211], v[138:141]
	v_mfma_f32_16x16x32_bf16 v[134:137], v[220:223], v[208:211], v[134:137]
	v_mfma_f32_16x16x32_bf16 v[130:133], v[224:227], v[208:211], v[130:133]
	ds_read_b128 v[208:211], v228 offset:8192
	s_waitcnt lgkmcnt(4)
; __device__ __forceinline__ float sigmoidf_(float x) { return 1.0f / (1.0f + __expf(-x)); }
; __device__ __forceinline__ float siluf_(float x) { return x / (1.0f + __expf(-x)); }
; __device__ __forceinline__ void phase_ffn_up(const Params& p, const u16* Wgu, u16* smem, volatile LAS unsigned* vb_) {
;     ...
; #pragma unroll
;     for (int i = 0; i < 8; ++i)
; #pragma unroll
;       for (int jp = 0; jp < 2; ++jp) {
; #pragma unroll
;         for (int r = 0; r < 4; ++r) {
;           const float g = acc[i][2 * jp][r], u = acc[i][2 * jp + 1][r];
;           smem[(wm * 128 + i * 16 + (lane >> 4) * 4 + r) * 136 + (wn * 2 + jp) * 16 + (lane & 15)] = f2bf(siluf_(g) * u);
;         }
;         __builtin_amdgcn_sched_barrier(0);
;       }
	v_mfma_f32_16x16x32_bf16 v[126:129], v[242:245], v[234:237], v[126:129]
	v_mfma_f32_16x16x32_bf16 v[122:125], v[246:249], v[234:237], v[122:125]
	v_mfma_f32_16x16x32_bf16 v[118:121], v[220:223], v[234:237], v[118:121]
	v_mfma_f32_16x16x32_bf16 v[114:117], v[224:227], v[234:237], v[114:117]
	ds_read_b128 v[234:237], v228 offset:10240
	s_waitcnt lgkmcnt(3)
	v_mfma_f32_16x16x32_bf16 v[110:113], v[242:245], v[238:241], v[110:113]
	v_mfma_f32_16x16x32_bf16 v[106:109], v[246:249], v[238:241], v[106:109]
	v_mfma_f32_16x16x32_bf16 v[102:105], v[220:223], v[238:241], v[102:105]
	v_mfma_f32_16x16x32_bf16 v[98:101], v[224:227], v[238:241], v[98:101]
	ds_read_b128 v[238:241], v228 offset:12288
	s_waitcnt lgkmcnt(2)
	v_mfma_f32_16x16x32_bf16 v[94:97], v[242:245], v[208:211], v[94:97]
	v_mfma_f32_16x16x32_bf16 v[90:93], v[246:249], v[208:211], v[90:93]
	v_mfma_f32_16x16x32_bf16 v[86:89], v[220:223], v[208:211], v[86:89]
	v_mfma_f32_16x16x32_bf16 v[82:85], v[224:227], v[208:211], v[82:85]
	ds_read_b128 v[208:211], v228 offset:14336
	s_waitcnt lgkmcnt(2)
	v_mfma_f32_16x16x32_bf16 v[78:81], v[242:245], v[234:237], v[78:81]
	v_mfma_f32_16x16x32_bf16 v[74:77], v[246:249], v[234:237], v[74:77]
	v_mfma_f32_16x16x32_bf16 v[70:73], v[220:223], v[234:237], v[70:73]
	v_mfma_f32_16x16x32_bf16 v[66:69], v[224:227], v[234:237], v[66:69]
	s_waitcnt lgkmcnt(1)
	v_mfma_f32_16x16x32_bf16 v[62:65], v[242:245], v[238:241], v[62:65]
	v_mfma_f32_16x16x32_bf16 v[58:61], v[246:249], v[238:241], v[58:61]
	v_mfma_f32_16x16x32_bf16 v[54:57], v[220:223], v[238:241], v[54:57]
	v_mfma_f32_16x16x32_bf16 v[50:53], v[224:227], v[238:241], v[50:53]
	s_waitcnt lgkmcnt(0)
	v_mfma_f32_16x16x32_bf16 v[46:49], v[242:245], v[208:211], v[46:49]
	v_mfma_f32_16x16x32_bf16 v[42:45], v[246:249], v[208:211], v[42:45]
	v_mfma_f32_16x16x32_bf16 v[38:41], v[220:223], v[208:211], v[38:41]
	v_mfma_f32_16x16x32_bf16 v[34:37], v[224:227], v[208:211], v[34:37]
	s_setprio 0
	s_add_i32 s43, s43, 1
	s_add_u32 s22, s22, 64
	s_addc_u32 s23, s23, 0
	s_addk_i32 s42, 0x4000
	s_cmpk_lg_i32 s22, 0x480
	s_barrier
	s_cbranch_scc1 .LBB0_601
	v_and_b32_e32 v228, 15, v175
	v_bfe_u32 v229, v175, 8, 1
	v_lshl_or_b32 v228, v229, 7, v228
	v_mul_u32_u24_e32 v228, 0x110, v228
	v_bfe_u32 v229, v175, 6, 2
	v_lshl_add_u32 v228, v229, 6, v228
	v_bfe_u32 v229, v175, 4, 2
	v_lshl_add_u32 v228, v229, 3, v228
	v_mul_f32_e32 v208, 0xbfb8aa3b, v158
	v_mul_f32_e32 v209, 0xbfb8aa3b, v159
	v_mul_f32_e32 v210, 0xbfb8aa3b, v160
	v_mul_f32_e32 v211, 0xbfb8aa3b, v161
	v_mul_f32_e32 v212, 0xbfb8aa3b, v150
	v_mul_f32_e32 v213, 0xbfb8aa3b, v151
	v_mul_f32_e32 v214, 0xbfb8aa3b, v152
	v_mul_f32_e32 v215, 0xbfb8aa3b, v153
	v_min_f32_e32 v208, 0x42fc0000, v208
	v_min_f32_e32 v209, 0x42fc0000, v209
	v_min_f32_e32 v210, 0x42fc0000, v210
	v_min_f32_e32 v211, 0x42fc0000, v211
	v_min_f32_e32 v212, 0x42fc0000, v212
	v_min_f32_e32 v213, 0x42fc0000, v213
	v_min_f32_e32 v214, 0x42fc0000, v214
	v_min_f32_e32 v215, 0x42fc0000, v215
	v_exp_f32_e32 v208, v208
	v_exp_f32_e32 v209, v209
	v_exp_f32_e32 v210, v210
	v_exp_f32_e32 v211, v211
	v_exp_f32_e32 v212, v212
	v_exp_f32_e32 v213, v213
	v_exp_f32_e32 v214, v214
	v_exp_f32_e32 v215, v215
	v_add_f32_e32 v208, 1.0, v208
	v_add_f32_e32 v209, 1.0, v209
	v_add_f32_e32 v210, 1.0, v210
	v_add_f32_e32 v211, 1.0, v211
	v_add_f32_e32 v212, 1.0, v212
	v_add_f32_e32 v213, 1.0, v213
	v_add_f32_e32 v214, 1.0, v214
	v_add_f32_e32 v215, 1.0, v215
	v_rcp_f32_e32 v216, v208
	v_rcp_f32_e32 v217, v209
	v_rcp_f32_e32 v218, v210
	v_rcp_f32_e32 v219, v211
	v_rcp_f32_e32 v220, v212
	v_rcp_f32_e32 v221, v213
	v_rcp_f32_e32 v222, v214
	v_rcp_f32_e32 v223, v215
	v_fma_f32 v208, -v208, v216, 1.0
	v_fma_f32 v209, -v209, v217, 1.0
	v_fma_f32 v210, -v210, v218, 1.0
	v_fma_f32 v211, -v211, v219, 1.0
	v_fma_f32 v212, -v212, v220, 1.0
	v_fma_f32 v213, -v213, v221, 1.0
	v_fma_f32 v214, -v214, v222, 1.0
	v_fma_f32 v215, -v215, v223, 1.0
	v_fmac_f32_e32 v216, v208, v216
	v_fmac_f32_e32 v217, v209, v217
	v_fmac_f32_e32 v218, v210, v218
	v_fmac_f32_e32 v219, v211, v219
	v_fmac_f32_e32 v220, v212, v220
	v_fmac_f32_e32 v221, v213, v221
	v_fmac_f32_e32 v222, v214, v222
	v_fmac_f32_e32 v223, v215, v223
	v_mul_f32_e32 v158, v158, v216
	v_mul_f32_e32 v159, v159, v217
	v_mul_f32_e32 v160, v160, v218
	v_mul_f32_e32 v161, v161, v219
	v_mul_f32_e32 v150, v150, v220
	v_mul_f32_e32 v151, v151, v221
	v_mul_f32_e32 v152, v152, v222
	v_mul_f32_e32 v153, v153, v223
	v_mul_f32_e32 v158, v158, v154
	v_mul_f32_e32 v159, v159, v155
	v_mul_f32_e32 v160, v160, v156
	v_mul_f32_e32 v161, v161, v157
	v_mul_f32_e32 v150, v150, v146
	v_mul_f32_e32 v151, v151, v147
	v_mul_f32_e32 v152, v152, v148
	v_mul_f32_e32 v153, v153, v149
	v_cvt_pk_bf16_f32 v158, v158, v159
	v_cvt_pk_bf16_f32 v159, v160, v161
	v_cvt_pk_bf16_f32 v150, v150, v151
	v_cvt_pk_bf16_f32 v151, v152, v153
	ds_write_b64 v228, v[158:159]
	ds_write_b64 v228, v[150:151] offset:32
	v_mul_f32_e32 v208, 0xbfb8aa3b, v142
	v_mul_f32_e32 v209, 0xbfb8aa3b, v143
	v_mul_f32_e32 v210, 0xbfb8aa3b, v144
	v_mul_f32_e32 v211, 0xbfb8aa3b, v145
	v_mul_f32_e32 v212, 0xbfb8aa3b, v134
	v_mul_f32_e32 v213, 0xbfb8aa3b, v135
	v_mul_f32_e32 v214, 0xbfb8aa3b, v136
	v_mul_f32_e32 v215, 0xbfb8aa3b, v137
	v_min_f32_e32 v208, 0x42fc0000, v208
	v_min_f32_e32 v209, 0x42fc0000, v209
	v_min_f32_e32 v210, 0x42fc0000, v210
	v_min_f32_e32 v211, 0x42fc0000, v211
	v_min_f32_e32 v212, 0x42fc0000, v212
	v_min_f32_e32 v213, 0x42fc0000, v213
	v_min_f32_e32 v214, 0x42fc0000, v214
	v_min_f32_e32 v215, 0x42fc0000, v215
	v_exp_f32_e32 v208, v208
	v_exp_f32_e32 v209, v209
	v_exp_f32_e32 v210, v210
	v_exp_f32_e32 v211, v211
	v_exp_f32_e32 v212, v212
; __device__ __forceinline__ float siluf_(float x) { return x / (1.0f + __expf(-x)); }
; __device__ __forceinline__ void phase_ffn_up(const Params& p, const u16* Wgu, u16* smem, volatile LAS unsigned* vb_) {
;     ...
; #pragma unroll
;     for (int i = 0; i < 8; ++i)
; #pragma unroll
;       for (int jp = 0; jp < 2; ++jp) {
; #pragma unroll
;         for (int r = 0; r < 4; ++r) {
;           const float g = acc[i][2 * jp][r], u = acc[i][2 * jp + 1][r];
;           smem[(wm * 128 + i * 16 + (lane >> 4) * 4 + r) * 136 + (wn * 2 + jp) * 16 + (lane & 15)] = f2bf(siluf_(g) * u);
;         }
;         __builtin_amdgcn_sched_barrier(0);
;       }
	v_exp_f32_e32 v213, v213
	v_exp_f32_e32 v214, v214
	v_exp_f32_e32 v215, v215
	v_add_f32_e32 v208, 1.0, v208
	v_add_f32_e32 v209, 1.0, v209
	v_add_f32_e32 v210, 1.0, v210
	v_add_f32_e32 v211, 1.0, v211
	v_add_f32_e32 v212, 1.0, v212
	v_add_f32_e32 v213, 1.0, v213
	v_add_f32_e32 v214, 1.0, v214
	v_add_f32_e32 v215, 1.0, v215
	v_rcp_f32_e32 v216, v208
	v_rcp_f32_e32 v217, v209
	v_rcp_f32_e32 v218, v210
	v_rcp_f32_e32 v219, v211
	v_rcp_f32_e32 v220, v212
	v_rcp_f32_e32 v221, v213
	v_rcp_f32_e32 v222, v214
	v_rcp_f32_e32 v223, v215
	v_fma_f32 v208, -v208, v216, 1.0
	v_fma_f32 v209, -v209, v217, 1.0
	v_fma_f32 v210, -v210, v218, 1.0
	v_fma_f32 v211, -v211, v219, 1.0
	v_fma_f32 v212, -v212, v220, 1.0
	v_fma_f32 v213, -v213, v221, 1.0
	v_fma_f32 v214, -v214, v222, 1.0
	v_fma_f32 v215, -v215, v223, 1.0
	v_fmac_f32_e32 v216, v208, v216
	v_fmac_f32_e32 v217, v209, v217
	v_fmac_f32_e32 v218, v210, v218
	v_fmac_f32_e32 v219, v211, v219
	v_fmac_f32_e32 v220, v212, v220
	v_fmac_f32_e32 v221, v213, v221
	v_fmac_f32_e32 v222, v214, v222
	v_fmac_f32_e32 v223, v215, v223
	v_mul_f32_e32 v142, v142, v216
	v_mul_f32_e32 v143, v143, v217
	v_mul_f32_e32 v144, v144, v218
	v_mul_f32_e32 v145, v145, v219
	v_mul_f32_e32 v134, v134, v220
	v_mul_f32_e32 v135, v135, v221
	v_mul_f32_e32 v136, v136, v222
	v_mul_f32_e32 v137, v137, v223
	v_mul_f32_e32 v142, v142, v138
	v_mul_f32_e32 v143, v143, v139
	v_mul_f32_e32 v144, v144, v140
	v_mul_f32_e32 v145, v145, v141
	v_mul_f32_e32 v134, v134, v130
	v_mul_f32_e32 v135, v135, v131
	v_mul_f32_e32 v136, v136, v132
	v_mul_f32_e32 v137, v137, v133
	v_cvt_pk_bf16_f32 v142, v142, v143
	v_cvt_pk_bf16_f32 v143, v144, v145
	v_cvt_pk_bf16_f32 v134, v134, v135
	v_cvt_pk_bf16_f32 v135, v136, v137
	ds_write_b64 v228, v[142:143] offset:4352
	ds_write_b64 v228, v[134:135] offset:4384
	v_mul_f32_e32 v208, 0xbfb8aa3b, v126
	v_mul_f32_e32 v209, 0xbfb8aa3b, v127
	v_mul_f32_e32 v210, 0xbfb8aa3b, v128
	v_mul_f32_e32 v211, 0xbfb8aa3b, v129
	v_mul_f32_e32 v212, 0xbfb8aa3b, v118
	v_mul_f32_e32 v213, 0xbfb8aa3b, v119
	v_mul_f32_e32 v214, 0xbfb8aa3b, v120
	v_mul_f32_e32 v215, 0xbfb8aa3b, v121
	v_min_f32_e32 v208, 0x42fc0000, v208
	v_min_f32_e32 v209, 0x42fc0000, v209
	v_min_f32_e32 v210, 0x42fc0000, v210
	v_min_f32_e32 v211, 0x42fc0000, v211
	v_min_f32_e32 v212, 0x42fc0000, v212
	v_min_f32_e32 v213, 0x42fc0000, v213
	v_min_f32_e32 v214, 0x42fc0000, v214
	v_min_f32_e32 v215, 0x42fc0000, v215
	v_exp_f32_e32 v208, v208
	v_exp_f32_e32 v209, v209
	v_exp_f32_e32 v210, v210
	v_exp_f32_e32 v211, v211
	v_exp_f32_e32 v212, v212
	v_exp_f32_e32 v213, v213
	v_exp_f32_e32 v214, v214
	v_exp_f32_e32 v215, v215
	v_add_f32_e32 v208, 1.0, v208
	v_add_f32_e32 v209, 1.0, v209
	v_add_f32_e32 v210, 1.0, v210
	v_add_f32_e32 v211, 1.0, v211
	v_add_f32_e32 v212, 1.0, v212
	v_add_f32_e32 v213, 1.0, v213
	v_add_f32_e32 v214, 1.0, v214
	v_add_f32_e32 v215, 1.0, v215
	v_rcp_f32_e32 v216, v208
	v_rcp_f32_e32 v217, v209
	v_rcp_f32_e32 v218, v210
	v_rcp_f32_e32 v219, v211
	v_rcp_f32_e32 v220, v212
	v_rcp_f32_e32 v221, v213
	v_rcp_f32_e32 v222, v214
	v_rcp_f32_e32 v223, v215
	v_fma_f32 v208, -v208, v216, 1.0
	v_fma_f32 v209, -v209, v217, 1.0
	v_fma_f32 v210, -v210, v218, 1.0
	v_fma_f32 v211, -v211, v219, 1.0
	v_fma_f32 v212, -v212, v220, 1.0
	v_fma_f32 v213, -v213, v221, 1.0
	v_fma_f32 v214, -v214, v222, 1.0
	v_fma_f32 v215, -v215, v223, 1.0
	v_fmac_f32_e32 v216, v208, v216
	v_fmac_f32_e32 v217, v209, v217
	v_fmac_f32_e32 v218, v210, v218
	v_fmac_f32_e32 v219, v211, v219
	v_fmac_f32_e32 v220, v212, v220
	v_fmac_f32_e32 v221, v213, v221
	v_fmac_f32_e32 v222, v214, v222
	v_fmac_f32_e32 v223, v215, v223
	v_mul_f32_e32 v126, v126, v216
	v_mul_f32_e32 v127, v127, v217
	v_mul_f32_e32 v128, v128, v218
	v_mul_f32_e32 v129, v129, v219
	v_mul_f32_e32 v118, v118, v220
	v_mul_f32_e32 v119, v119, v221
	v_mul_f32_e32 v120, v120, v222
	v_mul_f32_e32 v121, v121, v223
	v_mul_f32_e32 v126, v126, v122
	v_mul_f32_e32 v127, v127, v123
	v_mul_f32_e32 v128, v128, v124
	v_mul_f32_e32 v129, v129, v125
	v_mul_f32_e32 v118, v118, v114
	v_mul_f32_e32 v119, v119, v115
	v_mul_f32_e32 v120, v120, v116
	v_mul_f32_e32 v121, v121, v117
	v_cvt_pk_bf16_f32 v126, v126, v127
	v_cvt_pk_bf16_f32 v127, v128, v129
	v_cvt_pk_bf16_f32 v118, v118, v119
	v_cvt_pk_bf16_f32 v119, v120, v121
	ds_write_b64 v228, v[126:127] offset:8704
	ds_write_b64 v228, v[118:119] offset:8736
	v_mul_f32_e32 v208, 0xbfb8aa3b, v110
	v_mul_f32_e32 v209, 0xbfb8aa3b, v111
	v_mul_f32_e32 v210, 0xbfb8aa3b, v112
	v_mul_f32_e32 v211, 0xbfb8aa3b, v113
	v_mul_f32_e32 v212, 0xbfb8aa3b, v102
	v_mul_f32_e32 v213, 0xbfb8aa3b, v103
	v_mul_f32_e32 v214, 0xbfb8aa3b, v104
	v_mul_f32_e32 v215, 0xbfb8aa3b, v105
	v_min_f32_e32 v208, 0x42fc0000, v208
	v_min_f32_e32 v209, 0x42fc0000, v209
	v_min_f32_e32 v210, 0x42fc0000, v210
	v_min_f32_e32 v211, 0x42fc0000, v211
	v_min_f32_e32 v212, 0x42fc0000, v212
	v_min_f32_e32 v213, 0x42fc0000, v213
	v_min_f32_e32 v214, 0x42fc0000, v214
	v_min_f32_e32 v215, 0x42fc0000, v215
	v_exp_f32_e32 v208, v208
	v_exp_f32_e32 v209, v209
	v_exp_f32_e32 v210, v210
	v_exp_f32_e32 v211, v211
	v_exp_f32_e32 v212, v212
	v_exp_f32_e32 v213, v213
	v_exp_f32_e32 v214, v214
	v_exp_f32_e32 v215, v215
	v_add_f32_e32 v208, 1.0, v208
	v_add_f32_e32 v209, 1.0, v209
	v_add_f32_e32 v210, 1.0, v210
	v_add_f32_e32 v211, 1.0, v211
	v_add_f32_e32 v212, 1.0, v212
	v_add_f32_e32 v213, 1.0, v213
	v_add_f32_e32 v214, 1.0, v214
	v_add_f32_e32 v215, 1.0, v215
	v_rcp_f32_e32 v216, v208
	v_rcp_f32_e32 v217, v209
	v_rcp_f32_e32 v218, v210
	v_rcp_f32_e32 v219, v211
	v_rcp_f32_e32 v220, v212
	v_rcp_f32_e32 v221, v213
	v_rcp_f32_e32 v222, v214
	v_rcp_f32_e32 v223, v215
; __device__ __forceinline__ float siluf_(float x) { return x / (1.0f + __expf(-x)); }
; __device__ __forceinline__ void phase_ffn_up(const Params& p, const u16* Wgu, u16* smem, volatile LAS unsigned* vb_) {
;     ...
; #pragma unroll
;     for (int i = 0; i < 8; ++i)
; #pragma unroll
;       for (int jp = 0; jp < 2; ++jp) {
; #pragma unroll
;         for (int r = 0; r < 4; ++r) {
;           const float g = acc[i][2 * jp][r], u = acc[i][2 * jp + 1][r];
;           smem[(wm * 128 + i * 16 + (lane >> 4) * 4 + r) * 136 + (wn * 2 + jp) * 16 + (lane & 15)] = f2bf(siluf_(g) * u);
;         }
;         __builtin_amdgcn_sched_barrier(0);
;       }
	v_fma_f32 v208, -v208, v216, 1.0
	v_fma_f32 v209, -v209, v217, 1.0
	v_fma_f32 v210, -v210, v218, 1.0
	v_fma_f32 v211, -v211, v219, 1.0
	v_fma_f32 v212, -v212, v220, 1.0
	v_fma_f32 v213, -v213, v221, 1.0
	v_fma_f32 v214, -v214, v222, 1.0
	v_fma_f32 v215, -v215, v223, 1.0
	v_fmac_f32_e32 v216, v208, v216
	v_fmac_f32_e32 v217, v209, v217
	v_fmac_f32_e32 v218, v210, v218
	v_fmac_f32_e32 v219, v211, v219
	v_fmac_f32_e32 v220, v212, v220
	v_fmac_f32_e32 v221, v213, v221
	v_fmac_f32_e32 v222, v214, v222
	v_fmac_f32_e32 v223, v215, v223
	v_mul_f32_e32 v110, v110, v216
	v_mul_f32_e32 v111, v111, v217
	v_mul_f32_e32 v112, v112, v218
	v_mul_f32_e32 v113, v113, v219
	v_mul_f32_e32 v102, v102, v220
	v_mul_f32_e32 v103, v103, v221
	v_mul_f32_e32 v104, v104, v222
	v_mul_f32_e32 v105, v105, v223
	v_mul_f32_e32 v110, v110, v106
	v_mul_f32_e32 v111, v111, v107
	v_mul_f32_e32 v112, v112, v108
	v_mul_f32_e32 v113, v113, v109
	v_mul_f32_e32 v102, v102, v98
	v_mul_f32_e32 v103, v103, v99
	v_mul_f32_e32 v104, v104, v100
	v_mul_f32_e32 v105, v105, v101
	v_cvt_pk_bf16_f32 v110, v110, v111
	v_cvt_pk_bf16_f32 v111, v112, v113
	v_cvt_pk_bf16_f32 v102, v102, v103
	v_cvt_pk_bf16_f32 v103, v104, v105
	ds_write_b64 v228, v[110:111] offset:13056
	ds_write_b64 v228, v[102:103] offset:13088
	v_mul_f32_e32 v208, 0xbfb8aa3b, v94
	v_mul_f32_e32 v209, 0xbfb8aa3b, v95
	v_mul_f32_e32 v210, 0xbfb8aa3b, v96
	v_mul_f32_e32 v211, 0xbfb8aa3b, v97
	v_mul_f32_e32 v212, 0xbfb8aa3b, v86
	v_mul_f32_e32 v213, 0xbfb8aa3b, v87
	v_mul_f32_e32 v214, 0xbfb8aa3b, v88
	v_mul_f32_e32 v215, 0xbfb8aa3b, v89
	v_min_f32_e32 v208, 0x42fc0000, v208
	v_min_f32_e32 v209, 0x42fc0000, v209
	v_min_f32_e32 v210, 0x42fc0000, v210
	v_min_f32_e32 v211, 0x42fc0000, v211
	v_min_f32_e32 v212, 0x42fc0000, v212
	v_min_f32_e32 v213, 0x42fc0000, v213
	v_min_f32_e32 v214, 0x42fc0000, v214
	v_min_f32_e32 v215, 0x42fc0000, v215
	v_exp_f32_e32 v208, v208
	v_exp_f32_e32 v209, v209
	v_exp_f32_e32 v210, v210
	v_exp_f32_e32 v211, v211
	v_exp_f32_e32 v212, v212
	v_exp_f32_e32 v213, v213
	v_exp_f32_e32 v214, v214
	v_exp_f32_e32 v215, v215
	v_add_f32_e32 v208, 1.0, v208
	v_add_f32_e32 v209, 1.0, v209
	v_add_f32_e32 v210, 1.0, v210
	v_add_f32_e32 v211, 1.0, v211
	v_add_f32_e32 v212, 1.0, v212
	v_add_f32_e32 v213, 1.0, v213
	v_add_f32_e32 v214, 1.0, v214
	v_add_f32_e32 v215, 1.0, v215
	v_rcp_f32_e32 v216, v208
	v_rcp_f32_e32 v217, v209
	v_rcp_f32_e32 v218, v210
	v_rcp_f32_e32 v219, v211
	v_rcp_f32_e32 v220, v212
	v_rcp_f32_e32 v221, v213
	v_rcp_f32_e32 v222, v214
	v_rcp_f32_e32 v223, v215
	v_fma_f32 v208, -v208, v216, 1.0
	v_fma_f32 v209, -v209, v217, 1.0
	v_fma_f32 v210, -v210, v218, 1.0
	v_fma_f32 v211, -v211, v219, 1.0
	v_fma_f32 v212, -v212, v220, 1.0
	v_fma_f32 v213, -v213, v221, 1.0
	v_fma_f32 v214, -v214, v222, 1.0
	v_fma_f32 v215, -v215, v223, 1.0
	v_fmac_f32_e32 v216, v208, v216
	v_fmac_f32_e32 v217, v209, v217
	v_fmac_f32_e32 v218, v210, v218
	v_fmac_f32_e32 v219, v211, v219
	v_fmac_f32_e32 v220, v212, v220
	v_fmac_f32_e32 v221, v213, v221
	v_fmac_f32_e32 v222, v214, v222
	v_fmac_f32_e32 v223, v215, v223
	v_mul_f32_e32 v94, v94, v216
	v_mul_f32_e32 v95, v95, v217
	v_mul_f32_e32 v96, v96, v218
	v_mul_f32_e32 v97, v97, v219
	v_mul_f32_e32 v86, v86, v220
	v_mul_f32_e32 v87, v87, v221
	v_mul_f32_e32 v88, v88, v222
	v_mul_f32_e32 v89, v89, v223
	v_mul_f32_e32 v94, v94, v90
	v_mul_f32_e32 v95, v95, v91
	v_mul_f32_e32 v96, v96, v92
	v_mul_f32_e32 v97, v97, v93
	v_mul_f32_e32 v86, v86, v82
	v_mul_f32_e32 v87, v87, v83
	v_mul_f32_e32 v88, v88, v84
	v_mul_f32_e32 v89, v89, v85
	v_cvt_pk_bf16_f32 v94, v94, v95
	v_cvt_pk_bf16_f32 v95, v96, v97
	v_cvt_pk_bf16_f32 v86, v86, v87
	v_cvt_pk_bf16_f32 v87, v88, v89
	ds_write_b64 v228, v[94:95] offset:17408
	ds_write_b64 v228, v[86:87] offset:17440
	v_mul_f32_e32 v208, 0xbfb8aa3b, v78
	v_mul_f32_e32 v209, 0xbfb8aa3b, v79
	v_mul_f32_e32 v210, 0xbfb8aa3b, v80
	v_mul_f32_e32 v211, 0xbfb8aa3b, v81
	v_mul_f32_e32 v212, 0xbfb8aa3b, v70
	v_mul_f32_e32 v213, 0xbfb8aa3b, v71
	v_mul_f32_e32 v214, 0xbfb8aa3b, v72
	v_mul_f32_e32 v215, 0xbfb8aa3b, v73
	v_min_f32_e32 v208, 0x42fc0000, v208
	v_min_f32_e32 v209, 0x42fc0000, v209
	v_min_f32_e32 v210, 0x42fc0000, v210
	v_min_f32_e32 v211, 0x42fc0000, v211
	v_min_f32_e32 v212, 0x42fc0000, v212
	v_min_f32_e32 v213, 0x42fc0000, v213
	v_min_f32_e32 v214, 0x42fc0000, v214
	v_min_f32_e32 v215, 0x42fc0000, v215
	v_exp_f32_e32 v208, v208
	v_exp_f32_e32 v209, v209
	v_exp_f32_e32 v210, v210
	v_exp_f32_e32 v211, v211
	v_exp_f32_e32 v212, v212
	v_exp_f32_e32 v213, v213
	v_exp_f32_e32 v214, v214
	v_exp_f32_e32 v215, v215
	v_add_f32_e32 v208, 1.0, v208
	v_add_f32_e32 v209, 1.0, v209
	v_add_f32_e32 v210, 1.0, v210
	v_add_f32_e32 v211, 1.0, v211
	v_add_f32_e32 v212, 1.0, v212
	v_add_f32_e32 v213, 1.0, v213
	v_add_f32_e32 v214, 1.0, v214
	v_add_f32_e32 v215, 1.0, v215
	v_rcp_f32_e32 v216, v208
	v_rcp_f32_e32 v217, v209
	v_rcp_f32_e32 v218, v210
	v_rcp_f32_e32 v219, v211
	v_rcp_f32_e32 v220, v212
	v_rcp_f32_e32 v221, v213
	v_rcp_f32_e32 v222, v214
	v_rcp_f32_e32 v223, v215
	v_fma_f32 v208, -v208, v216, 1.0
	v_fma_f32 v209, -v209, v217, 1.0
	v_fma_f32 v210, -v210, v218, 1.0
	v_fma_f32 v211, -v211, v219, 1.0
	v_fma_f32 v212, -v212, v220, 1.0
	v_fma_f32 v213, -v213, v221, 1.0
	v_fma_f32 v214, -v214, v222, 1.0
	v_fma_f32 v215, -v215, v223, 1.0
	v_fmac_f32_e32 v216, v208, v216
	v_fmac_f32_e32 v217, v209, v217
	v_fmac_f32_e32 v218, v210, v218
	v_fmac_f32_e32 v219, v211, v219
	v_fmac_f32_e32 v220, v212, v220
	v_fmac_f32_e32 v221, v213, v221
	v_fmac_f32_e32 v222, v214, v222
	v_fmac_f32_e32 v223, v215, v223
	v_mul_f32_e32 v78, v78, v216
	v_mul_f32_e32 v79, v79, v217
; __device__ __forceinline__ float siluf_(float x) { return x / (1.0f + __expf(-x)); }
; __device__ __forceinline__ void phase_ffn_up(const Params& p, const u16* Wgu, u16* smem, volatile LAS unsigned* vb_) {
;     ...
; #pragma unroll
;     for (int i = 0; i < 8; ++i)
; #pragma unroll
;       for (int jp = 0; jp < 2; ++jp) {
; #pragma unroll
;         for (int r = 0; r < 4; ++r) {
;           const float g = acc[i][2 * jp][r], u = acc[i][2 * jp + 1][r];
;           smem[(wm * 128 + i * 16 + (lane >> 4) * 4 + r) * 136 + (wn * 2 + jp) * 16 + (lane & 15)] = f2bf(siluf_(g) * u);
;         }
;         __builtin_amdgcn_sched_barrier(0);
;       }
;     __syncthreads();
	v_mul_f32_e32 v80, v80, v218
	v_mul_f32_e32 v81, v81, v219
	v_mul_f32_e32 v70, v70, v220
	v_mul_f32_e32 v71, v71, v221
	v_mul_f32_e32 v72, v72, v222
	v_mul_f32_e32 v73, v73, v223
	v_mul_f32_e32 v78, v78, v74
	v_mul_f32_e32 v79, v79, v75
	v_mul_f32_e32 v80, v80, v76
	v_mul_f32_e32 v81, v81, v77
	v_mul_f32_e32 v70, v70, v66
	v_mul_f32_e32 v71, v71, v67
	v_mul_f32_e32 v72, v72, v68
	v_mul_f32_e32 v73, v73, v69
	v_cvt_pk_bf16_f32 v78, v78, v79
	v_cvt_pk_bf16_f32 v79, v80, v81
	v_cvt_pk_bf16_f32 v70, v70, v71
	v_cvt_pk_bf16_f32 v71, v72, v73
	ds_write_b64 v228, v[78:79] offset:21760
	ds_write_b64 v228, v[70:71] offset:21792
	v_mul_f32_e32 v208, 0xbfb8aa3b, v62
	v_mul_f32_e32 v209, 0xbfb8aa3b, v63
	v_mul_f32_e32 v210, 0xbfb8aa3b, v64
	v_mul_f32_e32 v211, 0xbfb8aa3b, v65
	v_mul_f32_e32 v212, 0xbfb8aa3b, v54
	v_mul_f32_e32 v213, 0xbfb8aa3b, v55
	v_mul_f32_e32 v214, 0xbfb8aa3b, v56
	v_mul_f32_e32 v215, 0xbfb8aa3b, v57
	v_min_f32_e32 v208, 0x42fc0000, v208
	v_min_f32_e32 v209, 0x42fc0000, v209
	v_min_f32_e32 v210, 0x42fc0000, v210
	v_min_f32_e32 v211, 0x42fc0000, v211
	v_min_f32_e32 v212, 0x42fc0000, v212
	v_min_f32_e32 v213, 0x42fc0000, v213
	v_min_f32_e32 v214, 0x42fc0000, v214
	v_min_f32_e32 v215, 0x42fc0000, v215
	v_exp_f32_e32 v208, v208
	v_exp_f32_e32 v209, v209
	v_exp_f32_e32 v210, v210
	v_exp_f32_e32 v211, v211
	v_exp_f32_e32 v212, v212
	v_exp_f32_e32 v213, v213
	v_exp_f32_e32 v214, v214
	v_exp_f32_e32 v215, v215
	v_add_f32_e32 v208, 1.0, v208
	v_add_f32_e32 v209, 1.0, v209
	v_add_f32_e32 v210, 1.0, v210
	v_add_f32_e32 v211, 1.0, v211
	v_add_f32_e32 v212, 1.0, v212
	v_add_f32_e32 v213, 1.0, v213
	v_add_f32_e32 v214, 1.0, v214
	v_add_f32_e32 v215, 1.0, v215
	v_rcp_f32_e32 v216, v208
	v_rcp_f32_e32 v217, v209
	v_rcp_f32_e32 v218, v210
	v_rcp_f32_e32 v219, v211
	v_rcp_f32_e32 v220, v212
	v_rcp_f32_e32 v221, v213
	v_rcp_f32_e32 v222, v214
	v_rcp_f32_e32 v223, v215
	v_fma_f32 v208, -v208, v216, 1.0
	v_fma_f32 v209, -v209, v217, 1.0
	v_fma_f32 v210, -v210, v218, 1.0
	v_fma_f32 v211, -v211, v219, 1.0
	v_fma_f32 v212, -v212, v220, 1.0
	v_fma_f32 v213, -v213, v221, 1.0
	v_fma_f32 v214, -v214, v222, 1.0
	v_fma_f32 v215, -v215, v223, 1.0
	v_fmac_f32_e32 v216, v208, v216
	v_fmac_f32_e32 v217, v209, v217
	v_fmac_f32_e32 v218, v210, v218
	v_fmac_f32_e32 v219, v211, v219
	v_fmac_f32_e32 v220, v212, v220
	v_fmac_f32_e32 v221, v213, v221
	v_fmac_f32_e32 v222, v214, v222
	v_fmac_f32_e32 v223, v215, v223
	v_mul_f32_e32 v62, v62, v216
	v_mul_f32_e32 v63, v63, v217
	v_mul_f32_e32 v64, v64, v218
	v_mul_f32_e32 v65, v65, v219
	v_mul_f32_e32 v54, v54, v220
	v_mul_f32_e32 v55, v55, v221
	v_mul_f32_e32 v56, v56, v222
	v_mul_f32_e32 v57, v57, v223
	v_mul_f32_e32 v62, v62, v58
	v_mul_f32_e32 v63, v63, v59
	v_mul_f32_e32 v64, v64, v60
	v_mul_f32_e32 v65, v65, v61
	v_mul_f32_e32 v54, v54, v50
	v_mul_f32_e32 v55, v55, v51
	v_mul_f32_e32 v56, v56, v52
	v_mul_f32_e32 v57, v57, v53
	v_cvt_pk_bf16_f32 v62, v62, v63
	v_cvt_pk_bf16_f32 v63, v64, v65
	v_cvt_pk_bf16_f32 v54, v54, v55
	v_cvt_pk_bf16_f32 v55, v56, v57
	ds_write_b64 v228, v[62:63] offset:26112
	ds_write_b64 v228, v[54:55] offset:26144
	v_mul_f32_e32 v208, 0xbfb8aa3b, v46
	v_mul_f32_e32 v209, 0xbfb8aa3b, v47
	v_mul_f32_e32 v210, 0xbfb8aa3b, v48
	v_mul_f32_e32 v211, 0xbfb8aa3b, v49
	v_mul_f32_e32 v212, 0xbfb8aa3b, v38
	v_mul_f32_e32 v213, 0xbfb8aa3b, v39
	v_mul_f32_e32 v214, 0xbfb8aa3b, v40
	v_mul_f32_e32 v215, 0xbfb8aa3b, v41
	v_min_f32_e32 v208, 0x42fc0000, v208
	v_min_f32_e32 v209, 0x42fc0000, v209
	v_min_f32_e32 v210, 0x42fc0000, v210
	v_min_f32_e32 v211, 0x42fc0000, v211
	v_min_f32_e32 v212, 0x42fc0000, v212
	v_min_f32_e32 v213, 0x42fc0000, v213
	v_min_f32_e32 v214, 0x42fc0000, v214
	v_min_f32_e32 v215, 0x42fc0000, v215
	v_exp_f32_e32 v208, v208
	v_exp_f32_e32 v209, v209
	v_exp_f32_e32 v210, v210
	v_exp_f32_e32 v211, v211
	v_exp_f32_e32 v212, v212
	v_exp_f32_e32 v213, v213
	v_exp_f32_e32 v214, v214
	v_exp_f32_e32 v215, v215
	v_add_f32_e32 v208, 1.0, v208
	v_add_f32_e32 v209, 1.0, v209
	v_add_f32_e32 v210, 1.0, v210
	v_add_f32_e32 v211, 1.0, v211
	v_add_f32_e32 v212, 1.0, v212
	v_add_f32_e32 v213, 1.0, v213
	v_add_f32_e32 v214, 1.0, v214
	v_add_f32_e32 v215, 1.0, v215
	v_rcp_f32_e32 v216, v208
	v_rcp_f32_e32 v217, v209
	v_rcp_f32_e32 v218, v210
	v_rcp_f32_e32 v219, v211
	v_rcp_f32_e32 v220, v212
	v_rcp_f32_e32 v221, v213
	v_rcp_f32_e32 v222, v214
	v_rcp_f32_e32 v223, v215
	v_fma_f32 v208, -v208, v216, 1.0
	v_fma_f32 v209, -v209, v217, 1.0
	v_fma_f32 v210, -v210, v218, 1.0
	v_fma_f32 v211, -v211, v219, 1.0
	v_fma_f32 v212, -v212, v220, 1.0
	v_fma_f32 v213, -v213, v221, 1.0
	v_fma_f32 v214, -v214, v222, 1.0
	v_fma_f32 v215, -v215, v223, 1.0
	v_fmac_f32_e32 v216, v208, v216
	v_fmac_f32_e32 v217, v209, v217
	v_fmac_f32_e32 v218, v210, v218
	v_fmac_f32_e32 v219, v211, v219
	v_fmac_f32_e32 v220, v212, v220
	v_fmac_f32_e32 v221, v213, v221
	v_fmac_f32_e32 v222, v214, v222
	v_fmac_f32_e32 v223, v215, v223
	v_mul_f32_e32 v46, v46, v216
	v_mul_f32_e32 v47, v47, v217
	v_mul_f32_e32 v48, v48, v218
	v_mul_f32_e32 v49, v49, v219
	v_mul_f32_e32 v38, v38, v220
	v_mul_f32_e32 v39, v39, v221
	v_mul_f32_e32 v40, v40, v222
	v_mul_f32_e32 v41, v41, v223
	v_mul_f32_e32 v46, v46, v42
	v_mul_f32_e32 v47, v47, v43
	v_mul_f32_e32 v48, v48, v44
	v_mul_f32_e32 v49, v49, v45
	v_mul_f32_e32 v38, v38, v34
	v_mul_f32_e32 v39, v39, v35
	v_mul_f32_e32 v40, v40, v36
	v_mul_f32_e32 v41, v41, v37
	v_cvt_pk_bf16_f32 v46, v46, v47
	v_cvt_pk_bf16_f32 v47, v48, v49
	v_cvt_pk_bf16_f32 v38, v38, v39
	v_cvt_pk_bf16_f32 v39, v40, v41
	ds_write_b64 v228, v[46:47] offset:30464
	ds_write_b64 v228, v[38:39] offset:30496
	s_waitcnt lgkmcnt(0)
	s_barrier
; __device__ __forceinline__ void phase_ffn_up(const Params& p, const u16* Wgu, u16* smem, volatile LAS unsigned* vb_) {
;     ...
;     __syncthreads();
; #pragma unroll
;     for (int k = 0; k < 8; ++k) {
;       const int c = tid + 512 * k;
;       const int row = c >> 4, ch = c & 15;
;       const uint4 v = *(const uint4*)(smem + row * 136 + ch * 8);
;       *(uint4*)(act + (size_t)(mt * 256 + row) * DFF + nt * 128 + ch * 8) = v;
;     }
;     __syncthreads();
	ds_read_b128 v[34:37], v197
	s_lshl_b32 s12, s40, 7
	s_ashr_i32 s13, s12, 31
	v_lshl_add_u64 v[38:39], s[12:13], 1, v[166:167]
	v_add_u32_e32 v40, s39, v189
	v_mad_i64_i32 v[40:41], s[12:13], v40, s7, v[38:39]
	s_waitcnt lgkmcnt(0)
	global_store_dwordx4 v[40:41], v[34:37], off
	ds_read_b128 v[34:37], v198
	v_add_u32_e32 v40, s39, v169
	v_mad_i64_i32 v[40:41], s[12:13], v40, s7, v[38:39]
	s_and_b64 vcc, exec, s[10:11]
	s_waitcnt lgkmcnt(0)
	global_store_dwordx4 v[40:41], v[34:37], off
	ds_read_b128 v[34:37], v199
	v_add_u32_e32 v40, s39, v190
	v_mad_i64_i32 v[40:41], s[12:13], v40, s7, v[38:39]
	s_mov_b32 s20, s41
	s_waitcnt lgkmcnt(0)
	global_store_dwordx4 v[40:41], v[34:37], off
	ds_read_b128 v[34:37], v200
	v_add_u32_e32 v40, s39, v191
	v_mad_i64_i32 v[40:41], s[12:13], v40, s7, v[38:39]
	s_waitcnt lgkmcnt(0)
	global_store_dwordx4 v[40:41], v[34:37], off
	ds_read_b128 v[34:37], v204
	v_add_u32_e32 v40, s39, v192
	v_mad_i64_i32 v[40:41], s[12:13], v40, s7, v[38:39]
	s_waitcnt lgkmcnt(0)
	global_store_dwordx4 v[40:41], v[34:37], off
	ds_read_b128 v[34:37], v205
	v_add_u32_e32 v40, s39, v193
	v_mad_i64_i32 v[40:41], s[12:13], v40, s7, v[38:39]
	s_waitcnt lgkmcnt(0)
	global_store_dwordx4 v[40:41], v[34:37], off
	ds_read_b128 v[34:37], v206
	v_add_u32_e32 v40, s39, v194
	v_mad_i64_i32 v[40:41], s[12:13], v40, s7, v[38:39]
	s_waitcnt lgkmcnt(0)
	global_store_dwordx4 v[40:41], v[34:37], off
	ds_read_b128 v[34:37], v207
	v_add_u32_e32 v40, s39, v195
	v_mad_i64_i32 v[38:39], s[12:13], v40, s7, v[38:39]
	s_mov_b64 s[12:13], -1
	s_waitcnt lgkmcnt(0)
	global_store_dwordx4 v[38:39], v[34:37], off
	s_barrier
	s_cbranch_vccz .LBB0_598
